# bf16 GEMM tile loops (in_proj, out_proj, down, sample up): first K iteration peeled so the first MFMA of each accumulator chain takes C=0 instead of 128 v_mov clears per tile
# speedup vs baseline: 1.0042x; 1.0042x over previous
.LBB0_124:
	s_ashr_i32 s67, s66, 31
	v_cmp_lt_i64_e32 vcc, s[12:13], v[140:141]
	s_lshl_b64 s[12:13], s[66:67], 19
	s_add_u32 s86, s23, s12
	s_addc_u32 s87, s24, s13
	s_and_b64 s[12:13], vcc, exec
	s_cselect_b32 s3, s87, s7
	s_cselect_b32 s5, s86, s6
	s_ashr_i32 s39, s38, 31
	s_lshl_b64 s[12:13], s[38:39], 19
	s_add_u32 s92, s58, s12
	s_addc_u32 s93, s59, s13
	s_and_b64 s[12:13], vcc, exec
	s_cselect_b32 s10, s93, s9
	s_cselect_b32 s12, s92, s8
	s_add_u32 s6, s6, 0x40080
	s_addc_u32 s7, s7, 0
	s_add_u32 s8, s8, 0x100
	s_addc_u32 s9, s9, 0
	s_mov_b32 s13, -2
	ds_read_b128 v[128:131], v165
	ds_read_b128 v[144:147], v165 offset:1024
	ds_read_b128 v[148:151], v165 offset:2048
	ds_read_b128 v[152:155], v165 offset:3072
	s_add_u32 s14, s6, 0xfffc0080
	s_addc_u32 s15, s7, -1
	s_cmp_eq_u32 s13, 12
	s_cselect_b32 s15, s3, s15
	s_cselect_b32 s14, s5, s14
	s_cselect_b32 s17, s10, s9
	s_cselect_b32 s16, s12, s8
	v_lshl_add_u64 v[194:195], s[6:7], 0, v[138:139]
	s_add_i32 m0, s27, 0xc000
	ds_read_b128 v[156:159], v166
	ds_read_b128 v[160:163], v166 offset:1024
	ds_read_b128 v[170:173], v166 offset:2048
	ds_read_b128 v[174:177], v166 offset:3072
	ds_read_b128 v[178:181], v166 offset:4096
	ds_read_b128 v[182:185], v166 offset:5120
	ds_read_b128 v[186:189], v166 offset:6144
	ds_read_b128 v[190:193], v166 offset:7168
	global_load_lds_dwordx4 v[194:195], off
	v_lshl_add_u64 v[194:195], v[194:195], 0, s[36:37]
	s_add_i32 m0, s27, 0xe000
	s_nop 0
	global_load_lds_dwordx4 v[194:195], off
	s_waitcnt lgkmcnt(8)
	s_barrier
	s_waitcnt lgkmcnt(0)
	s_setprio 1
	s_waitcnt lgkmcnt(0)
	v_mfma_f32_16x16x32_bf16 v[68:71], v[128:131], v[156:159], 0
	v_mfma_f32_16x16x32_bf16 v[64:67], v[148:151], v[156:159], 0
	v_mfma_f32_16x16x32_bf16 v[60:63], v[128:131], v[170:173], 0
	v_mfma_f32_16x16x32_bf16 v[56:59], v[148:151], v[170:173], 0
	v_mfma_f32_16x16x32_bf16 v[52:55], v[128:131], v[178:181], 0
	v_mfma_f32_16x16x32_bf16 v[48:51], v[148:151], v[178:181], 0
	v_mfma_f32_16x16x32_bf16 v[44:47], v[128:131], v[186:189], 0
	v_mfma_f32_16x16x32_bf16 v[40:43], v[148:151], v[186:189], 0
	v_mfma_f32_16x16x32_bf16 v[68:71], v[144:147], v[160:163], v[68:71]
	v_mfma_f32_16x16x32_bf16 v[64:67], v[152:155], v[160:163], v[64:67]
	v_mfma_f32_16x16x32_bf16 v[60:63], v[144:147], v[174:177], v[60:63]
	v_mfma_f32_16x16x32_bf16 v[56:59], v[152:155], v[174:177], v[56:59]
	v_mfma_f32_16x16x32_bf16 v[52:55], v[144:147], v[182:185], v[52:55]
	v_mfma_f32_16x16x32_bf16 v[48:51], v[152:155], v[182:185], v[48:51]
	v_mfma_f32_16x16x32_bf16 v[44:47], v[144:147], v[190:193], v[44:47]
	v_mfma_f32_16x16x32_bf16 v[40:43], v[152:155], v[190:193], v[40:43]
	s_setprio 0
	s_barrier
	v_lshl_add_u64 v[210:211], s[16:17], 0, v[134:135]
	s_add_i32 s16, s26, s25
	s_mov_b32 m0, s16
	ds_read_b128 v[194:197], v167
	ds_read_b128 v[198:201], v167 offset:1024
	ds_read_b128 v[202:205], v167 offset:2048
	ds_read_b128 v[206:209], v167 offset:3072
	global_load_lds_dwordx4 v[210:211], off
	v_lshl_add_u64 v[212:213], v[210:211], 0, s[36:37]
	s_add_i32 m0, s16, 0x2000
	s_nop 0
	global_load_lds_dwordx4 v[212:213], off
	s_barrier
	s_waitcnt lgkmcnt(0)
	s_setprio 1
	s_waitcnt lgkmcnt(0)
	v_mfma_f32_16x16x32_bf16 v[124:127], v[194:197], v[156:159], 0
	v_mfma_f32_16x16x32_bf16 v[120:123], v[202:205], v[156:159], 0
	v_mfma_f32_16x16x32_bf16 v[116:119], v[194:197], v[170:173], 0
	v_mfma_f32_16x16x32_bf16 v[112:115], v[202:205], v[170:173], 0
	v_mfma_f32_16x16x32_bf16 v[108:111], v[194:197], v[178:181], 0
	v_mfma_f32_16x16x32_bf16 v[104:107], v[202:205], v[178:181], 0
	v_mfma_f32_16x16x32_bf16 v[100:103], v[194:197], v[186:189], 0
	v_mfma_f32_16x16x32_bf16 v[96:99], v[202:205], v[186:189], 0
	v_mfma_f32_16x16x32_bf16 v[124:127], v[198:201], v[160:163], v[124:127]
	v_mfma_f32_16x16x32_bf16 v[120:123], v[206:209], v[160:163], v[120:123]
	v_mfma_f32_16x16x32_bf16 v[116:119], v[198:201], v[174:177], v[116:119]
	v_mfma_f32_16x16x32_bf16 v[112:115], v[206:209], v[174:177], v[112:115]
	v_mfma_f32_16x16x32_bf16 v[108:111], v[198:201], v[182:185], v[108:111]
	v_mfma_f32_16x16x32_bf16 v[104:107], v[206:209], v[182:185], v[104:107]
	v_mfma_f32_16x16x32_bf16 v[100:103], v[198:201], v[190:193], v[100:103]
	v_mfma_f32_16x16x32_bf16 v[96:99], v[206:209], v[190:193], v[96:99]
	s_setprio 0
	s_mov_b32 m0, s27
	v_lshl_add_u64 v[212:213], s[14:15], 0, v[132:133]
	s_barrier
	ds_read_b128 v[156:159], v166 offset:16384
	ds_read_b128 v[160:163], v166 offset:17408
	ds_read_b128 v[170:173], v166 offset:18432
	ds_read_b128 v[174:177], v166 offset:19456
	ds_read_b128 v[178:181], v166 offset:20480
	ds_read_b128 v[182:185], v166 offset:21504
	ds_read_b128 v[186:189], v166 offset:22528
	ds_read_b128 v[190:193], v166 offset:23552
	global_load_lds_dwordx4 v[212:213], off
	v_lshl_add_u64 v[214:215], v[212:213], 0, s[36:37]
	s_mov_b32 m0, s28
	s_nop 0
	global_load_lds_dwordx4 v[214:215], off
	s_barrier
	s_waitcnt lgkmcnt(0)
	s_setprio 1
	s_waitcnt lgkmcnt(0)
	v_mfma_f32_16x16x32_bf16 v[28:31], v[128:131], v[156:159], 0
	v_mfma_f32_16x16x32_bf16 v[24:27], v[148:151], v[156:159], 0
	v_mfma_f32_16x16x32_bf16 v[20:23], v[128:131], v[170:173], 0
	v_mfma_f32_16x16x32_bf16 v[16:19], v[148:151], v[170:173], 0
	v_mfma_f32_16x16x32_bf16 v[12:15], v[128:131], v[178:181], 0
	v_mfma_f32_16x16x32_bf16 v[8:11], v[148:151], v[178:181], 0
	v_mfma_f32_16x16x32_bf16 v[4:7], v[128:131], v[186:189], 0
	v_mfma_f32_16x16x32_bf16 v[0:3], v[148:151], v[186:189], 0
	v_mfma_f32_16x16x32_bf16 v[28:31], v[144:147], v[160:163], v[28:31]
	v_mfma_f32_16x16x32_bf16 v[24:27], v[152:155], v[160:163], v[24:27]
	v_mfma_f32_16x16x32_bf16 v[20:23], v[144:147], v[174:177], v[20:23]
	v_mfma_f32_16x16x32_bf16 v[16:19], v[152:155], v[174:177], v[16:19]
	v_mfma_f32_16x16x32_bf16 v[12:15], v[144:147], v[182:185], v[12:15]
	v_mfma_f32_16x16x32_bf16 v[8:11], v[152:155], v[182:185], v[8:11]
	v_mfma_f32_16x16x32_bf16 v[4:7], v[144:147], v[190:193], v[4:7]
	v_mfma_f32_16x16x32_bf16 v[0:3], v[152:155], v[190:193], v[0:3]
	s_setprio 0
	s_barrier
	s_add_i32 s14, s22, s25
	v_lshl_add_u64 v[128:129], v[210:211], 0, s[54:55]
	s_mov_b32 m0, s14
	s_nop 0
	global_load_lds_dwordx4 v[128:129], off
	v_lshl_add_u64 v[128:129], v[210:211], 0, s[60:61]
	s_add_i32 m0, s14, 0x2000
	s_nop 0
	global_load_lds_dwordx4 v[128:129], off
	s_waitcnt vmcnt(6)
	s_barrier
	s_setprio 1
	v_mfma_f32_16x16x32_bf16 v[92:95], v[194:197], v[156:159], 0
	v_mfma_f32_16x16x32_bf16 v[88:91], v[202:205], v[156:159], 0
	v_mfma_f32_16x16x32_bf16 v[84:87], v[194:197], v[170:173], 0
	v_mfma_f32_16x16x32_bf16 v[80:83], v[202:205], v[170:173], 0
	v_mfma_f32_16x16x32_bf16 v[76:79], v[194:197], v[178:181], 0
	v_mfma_f32_16x16x32_bf16 v[72:75], v[202:205], v[178:181], 0
	v_mfma_f32_16x16x32_bf16 v[36:39], v[194:197], v[186:189], 0
	v_mfma_f32_16x16x32_bf16 v[32:35], v[202:205], v[186:189], 0
	v_mfma_f32_16x16x32_bf16 v[92:95], v[198:201], v[160:163], v[92:95]
	v_mfma_f32_16x16x32_bf16 v[88:91], v[206:209], v[160:163], v[88:91]
	v_mfma_f32_16x16x32_bf16 v[84:87], v[198:201], v[174:177], v[84:87]
	v_mfma_f32_16x16x32_bf16 v[80:83], v[206:209], v[174:177], v[80:83]
	v_mfma_f32_16x16x32_bf16 v[76:79], v[198:201], v[182:185], v[76:79]
	v_mfma_f32_16x16x32_bf16 v[72:75], v[206:209], v[182:185], v[72:75]
	v_mfma_f32_16x16x32_bf16 v[36:39], v[198:201], v[190:193], v[36:39]
	v_mfma_f32_16x16x32_bf16 v[32:35], v[206:209], v[190:193], v[32:35]
	s_setprio 0
	s_add_i32 s14, 0, 0x18000
	v_add_u32_e32 v136, s14, v164
	s_barrier
	ds_read_b128 v[128:131], v136
	ds_read_b128 v[144:147], v136 offset:1024
	ds_read_b128 v[148:151], v136 offset:2048
	ds_read_b128 v[152:155], v136 offset:3072
	s_mov_b32 m0, s29
	v_lshl_add_u64 v[194:195], v[212:213], 0, s[54:55]
	ds_read_b128 v[156:159], v166 offset:32768
	ds_read_b128 v[160:163], v166 offset:33792
	ds_read_b128 v[170:173], v166 offset:34816
	ds_read_b128 v[174:177], v166 offset:35840
	ds_read_b128 v[178:181], v166 offset:36864
	ds_read_b128 v[182:185], v166 offset:37888
	ds_read_b128 v[186:189], v166 offset:38912
	ds_read_b128 v[190:193], v166 offset:39936
	global_load_lds_dwordx4 v[194:195], off
	v_lshl_add_u64 v[194:195], v[212:213], 0, s[60:61]
	s_mov_b32 m0, s33
	s_nop 0
	global_load_lds_dwordx4 v[194:195], off
	s_waitcnt lgkmcnt(8)
	s_barrier
	s_waitcnt lgkmcnt(0)
	s_setprio 1
	s_waitcnt lgkmcnt(0)
	v_mfma_f32_16x16x32_bf16 v[68:71], v[128:131], v[156:159], v[68:71]
	v_mfma_f32_16x16x32_bf16 v[64:67], v[148:151], v[156:159], v[64:67]
	v_mfma_f32_16x16x32_bf16 v[60:63], v[128:131], v[170:173], v[60:63]
	v_mfma_f32_16x16x32_bf16 v[56:59], v[148:151], v[170:173], v[56:59]
	v_mfma_f32_16x16x32_bf16 v[52:55], v[128:131], v[178:181], v[52:55]
	v_mfma_f32_16x16x32_bf16 v[48:51], v[148:151], v[178:181], v[48:51]
	v_mfma_f32_16x16x32_bf16 v[44:47], v[128:131], v[186:189], v[44:47]
	v_mfma_f32_16x16x32_bf16 v[40:43], v[148:151], v[186:189], v[40:43]
	v_mfma_f32_16x16x32_bf16 v[68:71], v[144:147], v[160:163], v[68:71]
	v_mfma_f32_16x16x32_bf16 v[64:67], v[152:155], v[160:163], v[64:67]
	v_mfma_f32_16x16x32_bf16 v[60:63], v[144:147], v[174:177], v[60:63]
	v_mfma_f32_16x16x32_bf16 v[56:59], v[152:155], v[174:177], v[56:59]
	v_mfma_f32_16x16x32_bf16 v[52:55], v[144:147], v[182:185], v[52:55]
	v_mfma_f32_16x16x32_bf16 v[48:51], v[152:155], v[182:185], v[48:51]
	v_mfma_f32_16x16x32_bf16 v[44:47], v[144:147], v[190:193], v[44:47]
	v_mfma_f32_16x16x32_bf16 v[40:43], v[152:155], v[190:193], v[40:43]
	s_setprio 0
	s_barrier
	s_add_i32 s15, 0, 0x1c000
	s_add_i32 s14, s14, s25
	v_add_u32_e32 v136, s15, v164
	v_lshl_add_u64 v[214:215], v[210:211], 0, s[90:91]
	s_mov_b32 m0, s14
	ds_read_b128 v[194:197], v136
	ds_read_b128 v[198:201], v136 offset:1024
	ds_read_b128 v[202:205], v136 offset:2048
	ds_read_b128 v[206:209], v136 offset:3072
	global_load_lds_dwordx4 v[214:215], off
	v_lshl_add_u64 v[214:215], v[210:211], 0, s[82:83]
	s_add_i32 m0, s14, 0x2000
	s_nop 0
	global_load_lds_dwordx4 v[214:215], off
	s_barrier
	s_waitcnt lgkmcnt(0)
	s_setprio 1
	s_waitcnt lgkmcnt(0)
	v_mfma_f32_16x16x32_bf16 v[124:127], v[194:197], v[156:159], v[124:127]
	v_mfma_f32_16x16x32_bf16 v[120:123], v[202:205], v[156:159], v[120:123]
	v_mfma_f32_16x16x32_bf16 v[116:119], v[194:197], v[170:173], v[116:119]
	v_mfma_f32_16x16x32_bf16 v[112:115], v[202:205], v[170:173], v[112:115]
	v_mfma_f32_16x16x32_bf16 v[108:111], v[194:197], v[178:181], v[108:111]
	v_mfma_f32_16x16x32_bf16 v[104:107], v[202:205], v[178:181], v[104:107]
	v_mfma_f32_16x16x32_bf16 v[100:103], v[194:197], v[186:189], v[100:103]
	v_mfma_f32_16x16x32_bf16 v[96:99], v[202:205], v[186:189], v[96:99]
	v_mfma_f32_16x16x32_bf16 v[124:127], v[198:201], v[160:163], v[124:127]
	v_mfma_f32_16x16x32_bf16 v[120:123], v[206:209], v[160:163], v[120:123]
	v_mfma_f32_16x16x32_bf16 v[116:119], v[198:201], v[174:177], v[116:119]
	v_mfma_f32_16x16x32_bf16 v[112:115], v[206:209], v[174:177], v[112:115]
	v_mfma_f32_16x16x32_bf16 v[108:111], v[198:201], v[182:185], v[108:111]
	v_mfma_f32_16x16x32_bf16 v[104:107], v[206:209], v[182:185], v[104:107]
	v_mfma_f32_16x16x32_bf16 v[100:103], v[198:201], v[190:193], v[100:103]
	v_mfma_f32_16x16x32_bf16 v[96:99], v[206:209], v[190:193], v[96:99]
	s_setprio 0
	s_mov_b32 m0, s74
	v_lshl_add_u64 v[214:215], v[212:213], 0, s[90:91]
	s_barrier
	ds_read_b128 v[156:159], v166 offset:49152
	ds_read_b128 v[160:163], v166 offset:50176
	ds_read_b128 v[170:173], v166 offset:51200
	ds_read_b128 v[174:177], v166 offset:52224
	ds_read_b128 v[178:181], v166 offset:53248
	ds_read_b128 v[182:185], v166 offset:54272
	ds_read_b128 v[186:189], v166 offset:55296
	ds_read_b128 v[190:193], v166 offset:56320
	global_load_lds_dwordx4 v[214:215], off
	v_lshl_add_u64 v[212:213], v[212:213], 0, s[82:83]
	s_mov_b32 m0, s75
	s_nop 0
	global_load_lds_dwordx4 v[212:213], off
	s_barrier
	s_waitcnt lgkmcnt(0)
	s_setprio 1
	s_waitcnt lgkmcnt(0)
	v_mfma_f32_16x16x32_bf16 v[28:31], v[128:131], v[156:159], v[28:31]
	v_mfma_f32_16x16x32_bf16 v[24:27], v[148:151], v[156:159], v[24:27]
	v_mfma_f32_16x16x32_bf16 v[20:23], v[128:131], v[170:173], v[20:23]
	v_mfma_f32_16x16x32_bf16 v[16:19], v[148:151], v[170:173], v[16:19]
	v_mfma_f32_16x16x32_bf16 v[12:15], v[128:131], v[178:181], v[12:15]
	v_mfma_f32_16x16x32_bf16 v[8:11], v[148:151], v[178:181], v[8:11]
	v_mfma_f32_16x16x32_bf16 v[4:7], v[128:131], v[186:189], v[4:7]
	v_mfma_f32_16x16x32_bf16 v[0:3], v[148:151], v[186:189], v[0:3]
	v_mfma_f32_16x16x32_bf16 v[28:31], v[144:147], v[160:163], v[28:31]
	v_mfma_f32_16x16x32_bf16 v[24:27], v[152:155], v[160:163], v[24:27]
	v_mfma_f32_16x16x32_bf16 v[20:23], v[144:147], v[174:177], v[20:23]
	v_mfma_f32_16x16x32_bf16 v[16:19], v[152:155], v[174:177], v[16:19]
	v_mfma_f32_16x16x32_bf16 v[12:15], v[144:147], v[182:185], v[12:15]
	v_mfma_f32_16x16x32_bf16 v[8:11], v[152:155], v[182:185], v[8:11]
	v_mfma_f32_16x16x32_bf16 v[4:7], v[144:147], v[190:193], v[4:7]
	v_mfma_f32_16x16x32_bf16 v[0:3], v[152:155], v[190:193], v[0:3]
	s_setprio 0
	s_barrier
	s_add_i32 s14, s15, s25
	v_lshl_add_u64 v[128:129], v[210:211], 0, s[84:85]
	s_mov_b32 m0, s14
	s_nop 0
	global_load_lds_dwordx4 v[128:129], off
	v_lshl_add_u64 v[128:129], v[210:211], 0, s[30:31]
	s_add_i32 m0, s14, 0x2000
	s_nop 0
	global_load_lds_dwordx4 v[128:129], off
	s_waitcnt vmcnt(6)
	s_barrier
	s_setprio 1
	v_mfma_f32_16x16x32_bf16 v[92:95], v[194:197], v[156:159], v[92:95]
	v_mfma_f32_16x16x32_bf16 v[88:91], v[202:205], v[156:159], v[88:91]
	v_mfma_f32_16x16x32_bf16 v[84:87], v[194:197], v[170:173], v[84:87]
	v_mfma_f32_16x16x32_bf16 v[80:83], v[202:205], v[170:173], v[80:83]
	v_mfma_f32_16x16x32_bf16 v[76:79], v[194:197], v[178:181], v[76:79]
	v_mfma_f32_16x16x32_bf16 v[72:75], v[202:205], v[178:181], v[72:75]
	v_mfma_f32_16x16x32_bf16 v[36:39], v[194:197], v[186:189], v[36:39]
	v_mfma_f32_16x16x32_bf16 v[32:35], v[202:205], v[186:189], v[32:35]
	v_mfma_f32_16x16x32_bf16 v[92:95], v[198:201], v[160:163], v[92:95]
	v_mfma_f32_16x16x32_bf16 v[88:91], v[206:209], v[160:163], v[88:91]
	v_mfma_f32_16x16x32_bf16 v[84:87], v[198:201], v[174:177], v[84:87]
	v_mfma_f32_16x16x32_bf16 v[80:83], v[206:209], v[174:177], v[80:83]
	v_mfma_f32_16x16x32_bf16 v[76:79], v[198:201], v[182:185], v[76:79]
	v_mfma_f32_16x16x32_bf16 v[72:75], v[206:209], v[182:185], v[72:75]
	v_mfma_f32_16x16x32_bf16 v[36:39], v[198:201], v[190:193], v[36:39]
	v_mfma_f32_16x16x32_bf16 v[32:35], v[206:209], v[190:193], v[32:35]
	s_setprio 0
	s_add_i32 s13, s13, 2
	s_add_u32 s6, s6, 0x100
	s_addc_u32 s7, s7, 0
	s_add_u32 s8, s8, 0x100
	s_addc_u32 s9, s9, 0
	s_cmp_gt_u32 s13, 13
	s_barrier

.LBB0_1429:
	v_mov_b32_e32 v4, v252
	s_waitcnt vmcnt(63) expcnt(7) lgkmcnt(15)
	v_readfirstlane_b32 s4, v4
	s_barrier
	s_ashr_i32 s10, s4, 6
	v_and_b32_e32 v173, 63, v4
	s_mul_i32 s5, s10, 0x410
	s_add_i32 s8, s5, 0
	s_add_i32 s11, s18, 0xffb9
	s_and_b32 s9, s11, 0xffff
	s_mul_i32 s2, s9, 0x8889
	s_lshr_b32 s2, s2, 22
	s_lshl_b32 s3, s2, 7
	s_mulk_i32 s2, 0x78
	s_sub_i32 s2, s11, s2
	s_add_i32 s2, s2, 8
	s_and_b32 s2, s2, 0xffff
	s_add_i32 s33, s3, s2
	s_lshr_b32 s2, s33, 7
	s_lshl_b32 s76, s2, 22
	s_lshl_b32 s2, s2, 3
	s_and_b32 s6, s4, 0xffffffc0
	s_add_i32 s2, s10, s2
	s_ashr_i32 s7, s6, 31
	s_ashr_i32 s3, s2, 31
	s_lshl_b64 s[2:3], s[2:3], 20
	s_lshl_b64 s[4:5], s[6:7], 1
	v_lshrrev_b32_e32 v5, 5, v173
	s_add_u32 s30, s95, s4
	v_and_b32_e32 v172, 31, v4
	s_addc_u32 s31, s22, s5
	v_lshlrev_b32_e32 v0, 4, v5
	v_lshl_add_u64 v[2:3], s[30:31], 0, v[0:1]
	v_lshl_or_b32 v0, s33, 6, v172
	v_lshlrev_b64 v[6:7], 10, v[0:1]
	v_or_b32_e32 v162, 32, v0
	v_mov_b32_e32 v163, v1
	v_lshl_add_u64 v[18:19], v[2:3], 0, v[6:7]
	v_lshlrev_b64 v[6:7], 10, v[162:163]
	s_waitcnt lgkmcnt(0)
	s_barrier
	v_lshl_add_u64 v[2:3], v[2:3], 0, v[6:7]
	global_load_dwordx4 v[6:9], v[18:19], off
	global_load_dwordx4 v[10:13], v[18:19], off offset:32
	global_load_dwordx4 v[14:17], v[18:19], off offset:64
	s_nop 0
	global_load_dwordx4 v[18:21], v[18:19], off offset:96
	s_nop 0
	global_load_dwordx4 v[22:25], v[2:3], off
	global_load_dwordx4 v[26:29], v[2:3], off offset:32
	global_load_dwordx4 v[30:33], v[2:3], off offset:64
	global_load_dwordx4 v[34:37], v[2:3], off offset:96
	s_mulk_i32 s10, 0x1bf0
	v_lshlrev_b32_e32 v38, 4, v173
	s_add_i32 s10, s8, s10
	v_and_b32_e32 v3, 32, v4
	v_add_u32_e32 v174, s10, v38
	s_lshl_b32 s10, s11, 16
	v_lshlrev_b32_e32 v2, 10, v172
	v_lshrrev_b32_e32 v3, 1, v3
	v_or3_b32 v2, s10, v2, v3
	s_lshl_b64 s[10:11], s[76:77], 1
	s_add_u32 s10, s10, s4
	v_mov_b32_e32 v3, v1
	s_addc_u32 s11, s11, s5
	v_lshl_add_u64 v[2:3], s[10:11], 0, v[2:3]
	s_mul_hi_u32 s10, s9, 0x2222223
	s_mul_hi_u32 s11, s10, 0x780000
	s_mul_i32 s30, s10, 0x780000
	v_subrev_co_u32_e32 v166, vcc, s30, v2
	v_mov_b32_e32 v2, s11
	s_lshl_b32 s9, s9, 13
	v_subb_co_u32_e32 v167, vcc, v3, v2, vcc
	s_add_u32 s2, s2, s9
	v_lshlrev_b32_e32 v2, 4, v172
	v_lshlrev_b32_e32 v3, 10, v5
	v_or3_b32 v2, v3, v2, s2
	s_addc_u32 s3, s3, 0
	v_or_b32_e32 v3, 0x200, v2
	s_mul_i32 s10, s10, 0xf0000
	v_mov_b32_e32 v4, s3
	v_subrev_co_u32_e32 v168, vcc, s10, v3
	v_lshlrev_b32_e32 v165, 2, v5
	s_nop 0
	v_subbrev_co_u32_e32 v169, vcc, 0, v4, vcc
	v_subrev_co_u32_e32 v170, vcc, s10, v2
	v_sub_u32_e32 v2, v172, v165
	s_nop 0
	v_subbrev_co_u32_e32 v171, vcc, 0, v4, vcc
	v_add_u32_e32 v177, 0x220, v2
	v_mov_b32_e32 v2, v1
	v_mov_b32_e32 v3, v1
	v_mov_b32_e32 v4, v1
	v_mov_b32_e32 v5, v1
	v_mov_b32_e32 v175, 0
	v_mov_b32_e32 v189, 0xf149f2ca
	s_mov_b32 s9, -1
	v_mov_b32_e32 v199, 0xf149f2ca
	v_mov_b32_e32 v176, 0
	v_readfirstlane_b32 s98, v252
	v_mbcnt_lo_u32_b32 v249, -1, 0
	v_mbcnt_hi_u32_b32 v249, -1, v249
	s_lshr_b32 s101, s98, 6
	s_lshl_b32 s98, s101, 13
	s_add_i32 s98, s98, 0x14000
	s_add_i32 s99, s98, 0x1c00
	s_mov_b32 s100, 0x1000
	s_cmp_eq_u32 s101, 7
	s_cselect_b32 s99, 0x3000, s99
	s_cselect_b32 s100, 0xfffe0400, s100
	v_and_b32_e32 v246, 31, v249
	v_lshrrev_b32_e32 v247, 5, v249
	v_bfe_u32 v248, v249, 1, 3
	v_lshl_add_u32 v250, v246, 7, s98
	v_xor_b32_e32 v241, v247, v248
	v_lshl_add_u32 v241, v241, 4, v250
	v_or_b32_e32 v242, 2, v247
	v_xor_b32_e32 v242, v242, v248
	v_lshl_add_u32 v242, v242, 4, v250
	v_or_b32_e32 v243, 4, v247
	v_xor_b32_e32 v243, v243, v248
	v_lshl_add_u32 v243, v243, 4, v250
	v_or_b32_e32 v244, 6, v247
	v_xor_b32_e32 v244, v244, v248
	v_lshl_add_u32 v244, v244, 4, v250
	v_mov_b32_e32 v245, 0x1000
	v_mov_b32_e32 v251, s100
	v_cmp_lt_u32_e32 vcc, 23, v246
	s_nop 1
	v_cndmask_b32_e32 v245, v245, v251, vcc
	v_add_u32_e32 v248, v244, v245
	v_add_u32_e32 v247, v243, v245
	v_add_u32_e32 v246, v242, v245
	v_add_u32_e32 v245, v241, v245
	v_lshrrev_b32_e32 v250, 3, v249
	v_lshlrev_b32_e32 v250, 10, v250
	v_and_b32_e32 v251, 7, v249
	v_lshrrev_b32_e32 v142, 4, v249
	v_xor_b32_e32 v251, v251, v142
	v_lshl_add_u32 v142, v251, 4, v250
	v_xor_b32_e32 v251, 4, v251
	v_lshl_add_u32 v250, v251, 4, v250
	v_add_u32_e32 v250, 0x2000, v250
	v_readfirstlane_b32 s100, v166
	v_readfirstlane_b32 s101, v167
	s_nop 0
	s_add_u32 s100, s100, s86
	s_addc_u32 s101, s101, s87
	s_add_u32 s100, s100, 0x85ee200
	s_addc_u32 s101, s101, 0
	v_mov_b32_e32 v143, 0
	v_mov_b32_e32 v251, 0
	v_lshl_add_u64 v[166:167], s[100:101], 0, v[142:143]
	v_lshl_add_u64 v[250:251], s[100:101], 0, v[250:251]
	s_mov_b64 s[100:101], 0x4000
	s_mov_b32 m0, s98
	s_nop 0
	global_load_lds_dwordx4 v[166:167], off
	s_add_i32 m0, s98, 0x400
	s_nop 0
	global_load_lds_dwordx4 v[250:251], off
	v_lshl_add_u64 v[142:143], v[166:167], 0, s[100:101]
	s_add_i32 m0, s98, 0x800
	s_nop 0
	global_load_lds_dwordx4 v[142:143], off
	v_lshl_add_u64 v[144:145], v[250:251], 0, s[100:101]
	s_add_i32 m0, s98, 0xc00
	s_nop 0
	global_load_lds_dwordx4 v[144:145], off
	v_lshl_add_u64 v[142:143], v[142:143], 0, s[100:101]
	s_add_i32 m0, s98, 0x1000
	s_nop 0
	global_load_lds_dwordx4 v[142:143], off
	v_lshl_add_u64 v[144:145], v[144:145], 0, s[100:101]
	s_add_i32 m0, s98, 0x1400
	s_nop 0
	global_load_lds_dwordx4 v[144:145], off
	v_lshl_add_u64 v[142:143], v[142:143], 0, s[100:101]
	s_add_i32 m0, s98, 0x1800
	s_nop 0
	global_load_lds_dwordx4 v[142:143], off
	v_lshl_add_u64 v[144:145], v[144:145], 0, s[100:101]
	s_mov_b32 m0, s99
	s_nop 0
	global_load_lds_dwordx4 v[144:145], off
	s_load_dwordx2 s[2:3], s[0:1], 0x40
	s_sub_i32 s10, s98, 0x14000
	s_lshr_b32 s10, s10, 13
	s_mul_i32 s10, s10, 0x101
	v_add_u32_e32 v44, s10, v173
	v_ashrrev_i32_e32 v45, 31, v44
	v_lshl_add_u32 v43, v173, 2, s8
	s_waitcnt lgkmcnt(0)
	v_lshl_add_u64 v[44:45], v[44:45], 2, s[2:3]
	global_load_dword v38, v[44:45], off
	global_load_dword v39, v[44:45], off offset:256
	global_load_dword v40, v[44:45], off offset:512
	global_load_dword v41, v[44:45], off offset:768
	v_cmp_eq_u32_e32 vcc, 0, v173
	s_and_saveexec_b64 s[2:3], vcc
	global_load_dword v42, v[44:45], off offset:1024
	s_waitcnt vmcnt(0)
	v_mul_f32_e32 v42, 0x3fb8aa3b, v42
	ds_write_b32 v43, v42 offset:1024
	ds_write_b32 v43, v42 offset:1028
	ds_write_b32 v43, v42 offset:1032
	ds_write_b32 v43, v42 offset:1036
	s_or_b64 exec, exec, s[2:3]
	v_mul_f32_e32 v38, 0x3fb8aa3b, v38
	v_mul_f32_e32 v39, 0x3fb8aa3b, v39
	v_mul_f32_e32 v40, 0x3fb8aa3b, v40
	v_mul_f32_e32 v41, 0x3fb8aa3b, v41
	ds_write_b32 v43, v38
	ds_write_b32 v43, v39 offset:256
	ds_write_b32 v43, v40 offset:512
	ds_write_b32 v43, v41 offset:768
	s_waitcnt vmcnt(7)
	s_waitcnt vmcnt(6)
	s_waitcnt vmcnt(5)
	s_waitcnt vmcnt(4)
	s_waitcnt vmcnt(3)
	s_waitcnt vmcnt(2)
	s_waitcnt vmcnt(1)
	s_waitcnt vmcnt(0)
	ds_write_b128 v174, v[6:9] offset:16384
	ds_write_b128 v174, v[10:13] offset:17408
	ds_write_b128 v174, v[14:17] offset:18432
	ds_write_b128 v174, v[18:21] offset:19456
	ds_write_b128 v174, v[22:25] offset:20480
	ds_write_b128 v174, v[26:29] offset:21504
	ds_write_b128 v174, v[30:33] offset:22528
	ds_write_b128 v174, v[34:37] offset:23552
	v_mov_b32_e32 v16, v1
	v_mov_b32_e32 v17, v1
	v_mov_b32_e32 v6, v1
	v_mov_b32_e32 v7, v1
	v_mov_b32_e32 v8, v1
	v_mov_b32_e32 v9, v1
	v_mov_b32_e32 v10, v1
	v_mov_b32_e32 v11, v1
	v_mov_b32_e32 v12, v1
	v_mov_b32_e32 v13, v1
	v_mov_b32_e32 v14, v1
	v_mov_b32_e32 v15, v1
	v_mov_b64_e32 v[48:49], v[16:17]
	v_mov_b64_e32 v[32:33], v[16:17]
	v_mov_b64_e32 v[64:65], v[16:17]
	v_mov_b64_e32 v[46:47], v[14:15]
	v_mov_b64_e32 v[44:45], v[12:13]
	v_mov_b64_e32 v[42:43], v[10:11]
	v_mov_b64_e32 v[40:41], v[8:9]
	v_mov_b64_e32 v[38:39], v[6:7]
	v_mov_b64_e32 v[36:37], v[4:5]
	v_mov_b64_e32 v[34:35], v[2:3]
	v_mov_b64_e32 v[30:31], v[14:15]
	v_mov_b64_e32 v[28:29], v[12:13]
	v_mov_b64_e32 v[26:27], v[10:11]
	v_mov_b64_e32 v[24:25], v[8:9]
	v_mov_b64_e32 v[22:23], v[6:7]
	v_mov_b64_e32 v[20:21], v[4:5]
	v_mov_b64_e32 v[18:19], v[2:3]
	v_mov_b64_e32 v[62:63], v[14:15]
	v_mov_b64_e32 v[60:61], v[12:13]
	v_mov_b64_e32 v[58:59], v[10:11]
	v_mov_b64_e32 v[56:57], v[8:9]
	v_mov_b64_e32 v[54:55], v[6:7]
	v_mov_b64_e32 v[52:53], v[4:5]
	v_mov_b64_e32 v[50:51], v[2:3]
	v_mov_b32_e32 v216, 0x3e38aa3b
	v_mov_b32_e32 v217, 0x3e38aa3b
	v_xor_b32_e32 v249, 32, v179
	v_lshlrev_b32_e32 v249, 2, v249

.LBB0_1931:
	s_ashr_i32 s19, s18, 31
	v_cmp_lt_i64_e32 vcc, s[20:21], v[198:199]
	s_lshl_b64 s[20:21], s[18:19], 19
	s_add_u32 s20, s31, s20
	s_addc_u32 s21, s33, s21
	s_and_b64 s[22:23], vcc, exec
	s_cselect_b32 s19, s21, s27
	s_cselect_b32 s56, s20, s26
	s_ashr_i32 s17, s16, 31
	s_lshl_b64 s[22:23], s[16:17], 19
	s_add_u32 s22, s15, s22
	s_addc_u32 s23, s30, s23
	s_and_b64 s[58:59], vcc, exec
	s_cselect_b32 s17, s23, s29
	s_cselect_b32 s57, s22, s28
	s_add_u32 s26, s26, 0x40080
	s_addc_u32 s27, s27, 0
	s_add_u32 s28, s28, 0x100
	s_addc_u32 s29, s29, 0
	s_mov_b32 s58, -2
	ds_read_b128 v[128:131], v218
	ds_read_b128 v[132:135], v218 offset:1024
	ds_read_b128 v[136:139], v218 offset:2048
	ds_read_b128 v[140:143], v218 offset:3072
	s_add_u32 s59, s26, 0xfffc0080
	s_addc_u32 s60, s27, -1
	s_cmp_eq_u32 s58, 12
	s_cselect_b32 s61, s19, s60
	s_cselect_b32 s60, s56, s59
	s_cselect_b32 s63, s17, s29
	s_cselect_b32 s62, s57, s28
	v_lshl_add_u64 v[176:177], s[26:27], 0, v[196:197]
	s_add_i32 m0, s36, 0xc000
	ds_read_b128 v[144:147], v219
	ds_read_b128 v[148:151], v219 offset:1024
	ds_read_b128 v[152:155], v219 offset:2048
	ds_read_b128 v[156:159], v219 offset:3072
	ds_read_b128 v[160:163], v219 offset:4096
	ds_read_b128 v[164:167], v219 offset:5120
	ds_read_b128 v[168:171], v219 offset:6144
	ds_read_b128 v[172:175], v219 offset:7168
	global_load_lds_dwordx4 v[176:177], off
	v_lshl_add_u64 v[176:177], v[176:177], 0, s[0:1]
	s_add_i32 m0, s36, 0xe000
	s_nop 0
	global_load_lds_dwordx4 v[176:177], off
	s_waitcnt lgkmcnt(8)
	s_barrier
	s_waitcnt lgkmcnt(0)
	s_setprio 1
	s_waitcnt lgkmcnt(0)
	v_mfma_f32_16x16x32_bf16 v[124:127], v[128:131], v[144:147], 0
	v_mfma_f32_16x16x32_bf16 v[120:123], v[136:139], v[144:147], 0
	v_mfma_f32_16x16x32_bf16 v[116:119], v[128:131], v[152:155], 0
	v_mfma_f32_16x16x32_bf16 v[112:115], v[136:139], v[152:155], 0
	v_mfma_f32_16x16x32_bf16 v[104:107], v[128:131], v[160:163], 0
	v_mfma_f32_16x16x32_bf16 v[92:95], v[136:139], v[160:163], 0
	v_mfma_f32_16x16x32_bf16 v[80:83], v[128:131], v[168:171], 0
	v_mfma_f32_16x16x32_bf16 v[72:75], v[136:139], v[168:171], 0
	v_mfma_f32_16x16x32_bf16 v[124:127], v[132:135], v[148:151], v[124:127]
	v_mfma_f32_16x16x32_bf16 v[120:123], v[140:143], v[148:151], v[120:123]
	v_mfma_f32_16x16x32_bf16 v[116:119], v[132:135], v[156:159], v[116:119]
	v_mfma_f32_16x16x32_bf16 v[112:115], v[140:143], v[156:159], v[112:115]
	v_mfma_f32_16x16x32_bf16 v[104:107], v[132:135], v[164:167], v[104:107]
	v_mfma_f32_16x16x32_bf16 v[92:95], v[140:143], v[164:167], v[92:95]
	v_mfma_f32_16x16x32_bf16 v[80:83], v[132:135], v[172:175], v[80:83]
	v_mfma_f32_16x16x32_bf16 v[72:75], v[140:143], v[172:175], v[72:75]
	s_setprio 0
	s_barrier
	s_add_i32 s59, s54, s35
	v_lshl_add_u64 v[202:203], s[62:63], 0, v[192:193]
	s_mov_b32 m0, s59
	ds_read_b128 v[176:179], v220
	ds_read_b128 v[180:183], v220 offset:1024
	ds_read_b128 v[184:187], v220 offset:2048
	ds_read_b128 v[188:191], v220 offset:3072
	global_load_lds_dwordx4 v[202:203], off
	v_lshl_add_u64 v[204:205], v[202:203], 0, s[0:1]
	s_add_i32 m0, s59, 0x2000
	s_nop 0
	global_load_lds_dwordx4 v[204:205], off
	s_barrier
	s_waitcnt lgkmcnt(0)
	s_setprio 1
	s_waitcnt lgkmcnt(0)
	v_mfma_f32_16x16x32_bf16 v[108:111], v[176:179], v[144:147], 0
	v_mfma_f32_16x16x32_bf16 v[100:103], v[184:187], v[144:147], 0
	v_mfma_f32_16x16x32_bf16 v[96:99], v[176:179], v[152:155], 0
	v_mfma_f32_16x16x32_bf16 v[88:91], v[184:187], v[152:155], 0
	v_mfma_f32_16x16x32_bf16 v[84:87], v[176:179], v[160:163], 0
	v_mfma_f32_16x16x32_bf16 v[76:79], v[184:187], v[160:163], 0
	v_mfma_f32_16x16x32_bf16 v[68:71], v[176:179], v[168:171], 0
	v_mfma_f32_16x16x32_bf16 v[64:67], v[184:187], v[168:171], 0
	v_mfma_f32_16x16x32_bf16 v[108:111], v[180:183], v[148:151], v[108:111]
	v_mfma_f32_16x16x32_bf16 v[100:103], v[188:191], v[148:151], v[100:103]
	v_mfma_f32_16x16x32_bf16 v[96:99], v[180:183], v[156:159], v[96:99]
	v_mfma_f32_16x16x32_bf16 v[88:91], v[188:191], v[156:159], v[88:91]
	v_mfma_f32_16x16x32_bf16 v[84:87], v[180:183], v[164:167], v[84:87]
	v_mfma_f32_16x16x32_bf16 v[76:79], v[188:191], v[164:167], v[76:79]
	v_mfma_f32_16x16x32_bf16 v[68:71], v[180:183], v[172:175], v[68:71]
	v_mfma_f32_16x16x32_bf16 v[64:67], v[188:191], v[172:175], v[64:67]
	s_setprio 0
	s_mov_b32 m0, s36
	v_lshl_add_u64 v[204:205], s[60:61], 0, v[192:193]
	s_barrier
	ds_read_b128 v[144:147], v219 offset:16384
	ds_read_b128 v[148:151], v219 offset:17408
	ds_read_b128 v[152:155], v219 offset:18432
	ds_read_b128 v[156:159], v219 offset:19456
	ds_read_b128 v[160:163], v219 offset:20480
	ds_read_b128 v[164:167], v219 offset:21504
	ds_read_b128 v[168:171], v219 offset:22528
	ds_read_b128 v[172:175], v219 offset:23552
	global_load_lds_dwordx4 v[204:205], off
	v_lshl_add_u64 v[206:207], v[204:205], 0, s[0:1]
	s_mov_b32 m0, s37
	s_nop 0
	global_load_lds_dwordx4 v[206:207], off
	s_barrier
	s_waitcnt lgkmcnt(0)
	s_setprio 1
	s_waitcnt lgkmcnt(0)
	v_mfma_f32_16x16x32_bf16 v[60:63], v[128:131], v[144:147], 0
	v_mfma_f32_16x16x32_bf16 v[56:59], v[136:139], v[144:147], 0
	v_mfma_f32_16x16x32_bf16 v[44:47], v[128:131], v[152:155], 0
	v_mfma_f32_16x16x32_bf16 v[40:43], v[136:139], v[152:155], 0
	v_mfma_f32_16x16x32_bf16 v[28:31], v[128:131], v[160:163], 0
	v_mfma_f32_16x16x32_bf16 v[24:27], v[136:139], v[160:163], 0
	v_mfma_f32_16x16x32_bf16 v[16:19], v[128:131], v[168:171], 0
	v_mfma_f32_16x16x32_bf16 v[8:11], v[136:139], v[168:171], 0
	v_mfma_f32_16x16x32_bf16 v[60:63], v[132:135], v[148:151], v[60:63]
	v_mfma_f32_16x16x32_bf16 v[56:59], v[140:143], v[148:151], v[56:59]
	v_mfma_f32_16x16x32_bf16 v[44:47], v[132:135], v[156:159], v[44:47]
	v_mfma_f32_16x16x32_bf16 v[40:43], v[140:143], v[156:159], v[40:43]
	v_mfma_f32_16x16x32_bf16 v[28:31], v[132:135], v[164:167], v[28:31]
	v_mfma_f32_16x16x32_bf16 v[24:27], v[140:143], v[164:167], v[24:27]
	v_mfma_f32_16x16x32_bf16 v[16:19], v[132:135], v[172:175], v[16:19]
	v_mfma_f32_16x16x32_bf16 v[8:11], v[140:143], v[172:175], v[8:11]
	s_setprio 0
	s_barrier
	s_add_i32 s59, s55, s35
	v_lshl_add_u64 v[128:129], v[202:203], 0, s[4:5]
	s_mov_b32 m0, s59
	s_nop 0
	global_load_lds_dwordx4 v[128:129], off
	v_lshl_add_u64 v[128:129], v[202:203], 0, s[6:7]
	s_add_i32 m0, s59, 0x2000
	s_nop 0
	global_load_lds_dwordx4 v[128:129], off
	s_waitcnt vmcnt(6)
	s_barrier
	s_setprio 1
	v_mfma_f32_16x16x32_bf16 v[52:55], v[176:179], v[144:147], 0
	v_mfma_f32_16x16x32_bf16 v[48:51], v[184:187], v[144:147], 0
	v_mfma_f32_16x16x32_bf16 v[36:39], v[176:179], v[152:155], 0
	v_mfma_f32_16x16x32_bf16 v[32:35], v[184:187], v[152:155], 0
	v_mfma_f32_16x16x32_bf16 v[20:23], v[176:179], v[160:163], 0
	v_mfma_f32_16x16x32_bf16 v[12:15], v[184:187], v[160:163], 0
	v_mfma_f32_16x16x32_bf16 v[4:7], v[176:179], v[168:171], 0
	v_mfma_f32_16x16x32_bf16 v[0:3], v[184:187], v[168:171], 0
	v_mfma_f32_16x16x32_bf16 v[52:55], v[180:183], v[148:151], v[52:55]
	v_mfma_f32_16x16x32_bf16 v[48:51], v[188:191], v[148:151], v[48:51]
	v_mfma_f32_16x16x32_bf16 v[36:39], v[180:183], v[156:159], v[36:39]
	v_mfma_f32_16x16x32_bf16 v[32:35], v[188:191], v[156:159], v[32:35]
	v_mfma_f32_16x16x32_bf16 v[20:23], v[180:183], v[164:167], v[20:23]
	v_mfma_f32_16x16x32_bf16 v[12:15], v[188:191], v[164:167], v[12:15]
	v_mfma_f32_16x16x32_bf16 v[4:7], v[180:183], v[172:175], v[4:7]
	v_mfma_f32_16x16x32_bf16 v[0:3], v[188:191], v[172:175], v[0:3]
	s_setprio 0
	s_add_i32 s59, 0, 0x18000
	v_add_u32_e32 v140, s59, v217
	s_barrier
	ds_read_b128 v[128:131], v140
	ds_read_b128 v[132:135], v140 offset:1024
	ds_read_b128 v[136:139], v140 offset:2048
	ds_read_b128 v[140:143], v140 offset:3072
	s_mov_b32 m0, s38
	v_lshl_add_u64 v[176:177], v[204:205], 0, s[4:5]
	ds_read_b128 v[144:147], v219 offset:32768
	ds_read_b128 v[148:151], v219 offset:33792
	ds_read_b128 v[152:155], v219 offset:34816
	ds_read_b128 v[156:159], v219 offset:35840
	ds_read_b128 v[160:163], v219 offset:36864
	ds_read_b128 v[164:167], v219 offset:37888
	ds_read_b128 v[168:171], v219 offset:38912
	ds_read_b128 v[172:175], v219 offset:39936
	global_load_lds_dwordx4 v[176:177], off
	v_lshl_add_u64 v[176:177], v[204:205], 0, s[6:7]
	s_mov_b32 m0, s39
	s_nop 0
	global_load_lds_dwordx4 v[176:177], off
	s_waitcnt lgkmcnt(8)
	s_barrier
	s_waitcnt lgkmcnt(0)
	s_setprio 1
	s_waitcnt lgkmcnt(0)
	v_mfma_f32_16x16x32_bf16 v[124:127], v[128:131], v[144:147], v[124:127]
	v_mfma_f32_16x16x32_bf16 v[120:123], v[136:139], v[144:147], v[120:123]
	v_mfma_f32_16x16x32_bf16 v[116:119], v[128:131], v[152:155], v[116:119]
	v_mfma_f32_16x16x32_bf16 v[112:115], v[136:139], v[152:155], v[112:115]
	v_mfma_f32_16x16x32_bf16 v[104:107], v[128:131], v[160:163], v[104:107]
	v_mfma_f32_16x16x32_bf16 v[92:95], v[136:139], v[160:163], v[92:95]
	v_mfma_f32_16x16x32_bf16 v[80:83], v[128:131], v[168:171], v[80:83]
	v_mfma_f32_16x16x32_bf16 v[72:75], v[136:139], v[168:171], v[72:75]
	v_mfma_f32_16x16x32_bf16 v[124:127], v[132:135], v[148:151], v[124:127]
	v_mfma_f32_16x16x32_bf16 v[120:123], v[140:143], v[148:151], v[120:123]
	v_mfma_f32_16x16x32_bf16 v[116:119], v[132:135], v[156:159], v[116:119]
	v_mfma_f32_16x16x32_bf16 v[112:115], v[140:143], v[156:159], v[112:115]
	v_mfma_f32_16x16x32_bf16 v[104:107], v[132:135], v[164:167], v[104:107]
	v_mfma_f32_16x16x32_bf16 v[92:95], v[140:143], v[164:167], v[92:95]
	v_mfma_f32_16x16x32_bf16 v[80:83], v[132:135], v[172:175], v[80:83]
	v_mfma_f32_16x16x32_bf16 v[72:75], v[140:143], v[172:175], v[72:75]
	s_setprio 0
	s_barrier
	s_add_i32 s60, 0, 0x1c000
	s_add_i32 s59, s59, s35
	v_add_u32_e32 v188, s60, v217
	v_lshl_add_u64 v[206:207], v[202:203], 0, s[2:3]
	s_mov_b32 m0, s59
	ds_read_b128 v[176:179], v188
	ds_read_b128 v[180:183], v188 offset:1024
	ds_read_b128 v[184:187], v188 offset:2048
	ds_read_b128 v[188:191], v188 offset:3072
	global_load_lds_dwordx4 v[206:207], off
	v_lshl_add_u64 v[206:207], v[202:203], 0, s[8:9]
	s_add_i32 m0, s59, 0x2000
	s_nop 0
	global_load_lds_dwordx4 v[206:207], off
	s_barrier
	s_waitcnt lgkmcnt(0)
	s_setprio 1
	s_waitcnt lgkmcnt(0)
	v_mfma_f32_16x16x32_bf16 v[108:111], v[176:179], v[144:147], v[108:111]
	v_mfma_f32_16x16x32_bf16 v[100:103], v[184:187], v[144:147], v[100:103]
	v_mfma_f32_16x16x32_bf16 v[96:99], v[176:179], v[152:155], v[96:99]
	v_mfma_f32_16x16x32_bf16 v[88:91], v[184:187], v[152:155], v[88:91]
	v_mfma_f32_16x16x32_bf16 v[84:87], v[176:179], v[160:163], v[84:87]
	v_mfma_f32_16x16x32_bf16 v[76:79], v[184:187], v[160:163], v[76:79]
	v_mfma_f32_16x16x32_bf16 v[68:71], v[176:179], v[168:171], v[68:71]
	v_mfma_f32_16x16x32_bf16 v[64:67], v[184:187], v[168:171], v[64:67]
	v_mfma_f32_16x16x32_bf16 v[108:111], v[180:183], v[148:151], v[108:111]
	v_mfma_f32_16x16x32_bf16 v[100:103], v[188:191], v[148:151], v[100:103]
	v_mfma_f32_16x16x32_bf16 v[96:99], v[180:183], v[156:159], v[96:99]
	v_mfma_f32_16x16x32_bf16 v[88:91], v[188:191], v[156:159], v[88:91]
	v_mfma_f32_16x16x32_bf16 v[84:87], v[180:183], v[164:167], v[84:87]
	v_mfma_f32_16x16x32_bf16 v[76:79], v[188:191], v[164:167], v[76:79]
	v_mfma_f32_16x16x32_bf16 v[68:71], v[180:183], v[172:175], v[68:71]
	v_mfma_f32_16x16x32_bf16 v[64:67], v[188:191], v[172:175], v[64:67]
	s_setprio 0
	s_mov_b32 m0, s52
	v_lshl_add_u64 v[206:207], v[204:205], 0, s[2:3]
	s_barrier
	ds_read_b128 v[144:147], v219 offset:49152
	ds_read_b128 v[148:151], v219 offset:50176
	ds_read_b128 v[152:155], v219 offset:51200
	ds_read_b128 v[156:159], v219 offset:52224
	ds_read_b128 v[160:163], v219 offset:53248
	ds_read_b128 v[164:167], v219 offset:54272
	ds_read_b128 v[168:171], v219 offset:55296
	ds_read_b128 v[172:175], v219 offset:56320
	global_load_lds_dwordx4 v[206:207], off
	v_lshl_add_u64 v[204:205], v[204:205], 0, s[8:9]
	s_mov_b32 m0, s53
	s_nop 0
	global_load_lds_dwordx4 v[204:205], off
	s_barrier
	s_waitcnt lgkmcnt(0)
	s_setprio 1
	s_waitcnt lgkmcnt(0)
	v_mfma_f32_16x16x32_bf16 v[60:63], v[128:131], v[144:147], v[60:63]
	v_mfma_f32_16x16x32_bf16 v[56:59], v[136:139], v[144:147], v[56:59]
	v_mfma_f32_16x16x32_bf16 v[44:47], v[128:131], v[152:155], v[44:47]
	v_mfma_f32_16x16x32_bf16 v[40:43], v[136:139], v[152:155], v[40:43]
	v_mfma_f32_16x16x32_bf16 v[28:31], v[128:131], v[160:163], v[28:31]
	v_mfma_f32_16x16x32_bf16 v[24:27], v[136:139], v[160:163], v[24:27]
	v_mfma_f32_16x16x32_bf16 v[16:19], v[128:131], v[168:171], v[16:19]
	v_mfma_f32_16x16x32_bf16 v[8:11], v[136:139], v[168:171], v[8:11]
	v_mfma_f32_16x16x32_bf16 v[60:63], v[132:135], v[148:151], v[60:63]
	v_mfma_f32_16x16x32_bf16 v[56:59], v[140:143], v[148:151], v[56:59]
	v_mfma_f32_16x16x32_bf16 v[44:47], v[132:135], v[156:159], v[44:47]
	v_mfma_f32_16x16x32_bf16 v[40:43], v[140:143], v[156:159], v[40:43]
	v_mfma_f32_16x16x32_bf16 v[28:31], v[132:135], v[164:167], v[28:31]
	v_mfma_f32_16x16x32_bf16 v[24:27], v[140:143], v[164:167], v[24:27]
	v_mfma_f32_16x16x32_bf16 v[16:19], v[132:135], v[172:175], v[16:19]
	v_mfma_f32_16x16x32_bf16 v[8:11], v[140:143], v[172:175], v[8:11]
	s_setprio 0
	s_barrier
	s_add_i32 s59, s60, s35
	v_lshl_add_u64 v[128:129], v[202:203], 0, s[10:11]
	s_mov_b32 m0, s59
	s_nop 0
	global_load_lds_dwordx4 v[128:129], off
	v_lshl_add_u64 v[128:129], v[202:203], 0, s[12:13]
	s_add_i32 m0, s59, 0x2000
	s_nop 0
	global_load_lds_dwordx4 v[128:129], off
	s_waitcnt vmcnt(6)
	s_barrier
	s_setprio 1
	v_mfma_f32_16x16x32_bf16 v[52:55], v[176:179], v[144:147], v[52:55]
	v_mfma_f32_16x16x32_bf16 v[48:51], v[184:187], v[144:147], v[48:51]
	v_mfma_f32_16x16x32_bf16 v[36:39], v[176:179], v[152:155], v[36:39]
	v_mfma_f32_16x16x32_bf16 v[32:35], v[184:187], v[152:155], v[32:35]
	v_mfma_f32_16x16x32_bf16 v[20:23], v[176:179], v[160:163], v[20:23]
	v_mfma_f32_16x16x32_bf16 v[12:15], v[184:187], v[160:163], v[12:15]
	v_mfma_f32_16x16x32_bf16 v[4:7], v[176:179], v[168:171], v[4:7]
	v_mfma_f32_16x16x32_bf16 v[0:3], v[184:187], v[168:171], v[0:3]
	v_mfma_f32_16x16x32_bf16 v[52:55], v[180:183], v[148:151], v[52:55]
	v_mfma_f32_16x16x32_bf16 v[48:51], v[188:191], v[148:151], v[48:51]
	v_mfma_f32_16x16x32_bf16 v[36:39], v[180:183], v[156:159], v[36:39]
	v_mfma_f32_16x16x32_bf16 v[32:35], v[188:191], v[156:159], v[32:35]
	v_mfma_f32_16x16x32_bf16 v[20:23], v[180:183], v[164:167], v[20:23]
	v_mfma_f32_16x16x32_bf16 v[12:15], v[188:191], v[164:167], v[12:15]
	v_mfma_f32_16x16x32_bf16 v[4:7], v[180:183], v[172:175], v[4:7]
	v_mfma_f32_16x16x32_bf16 v[0:3], v[188:191], v[172:175], v[0:3]
	s_setprio 0
	s_add_i32 s58, s58, 2
	s_add_u32 s26, s26, 0x100
	s_addc_u32 s27, s27, 0
	s_add_u32 s28, s28, 0x100
	s_addc_u32 s29, s29, 0
	s_cmp_gt_u32 s58, 13
	s_barrier

.LBB0_2100:
	s_lshl_b32 s44, s22, 8
	s_ashr_i32 s45, s44, 31
	s_lshl_b64 s[44:45], s[44:45], 11
	s_add_u32 s23, s56, s44
	s_addc_u32 s44, s57, s45
	s_add_u32 s52, s23, 0x4000000
	v_cmp_lt_i64_e64 s[20:21], s[20:21], 42
	s_addc_u32 s53, s44, 0
	s_and_b64 s[44:45], s[20:21], exec
	s_cselect_b32 s23, s53, s3
	s_cselect_b32 s44, s52, s2
	s_ashr_i32 s51, s50, 31
	s_lshl_b64 s[54:55], s[50:51], 19
	s_add_u32 s54, s24, s54
	s_addc_u32 s55, s25, s55
	s_and_b64 s[20:21], s[20:21], exec
	s_cselect_b32 s20, s55, s19
	s_cselect_b32 s21, s54, s18
	s_add_u32 s2, s2, 0x42080
	s_addc_u32 s3, s3, 0
	s_add_u32 s18, s18, 0x100
	s_addc_u32 s19, s19, 0
	s_mov_b32 s45, -2
	ds_read_b128 v[128:131], v203
	ds_read_b128 v[132:135], v203 offset:1024
	ds_read_b128 v[136:139], v203 offset:2048
	ds_read_b128 v[140:143], v203 offset:3072
	s_add_u32 s51, s2, 0xfffbe080
	s_addc_u32 s81, s3, -1
	s_cmp_eq_u32 s45, 12
	s_cselect_b32 s83, s23, s81
	s_cselect_b32 s82, s44, s51
	s_cselect_b32 s85, s20, s19
	s_cselect_b32 s84, s21, s18
	s_mov_b32 s86, 0xfffc0000
	v_lshl_add_u64 v[182:183], s[2:3], 0, v[180:181]
	s_mov_b32 s87, -1
	v_lshl_add_u64 v[184:185], v[182:183], 0, s[86:87]
	s_add_i32 m0, s68, 0xc000
	ds_read_b128 v[144:147], v204
	ds_read_b128 v[148:151], v204 offset:1024
	ds_read_b128 v[152:155], v204 offset:2048
	ds_read_b128 v[156:159], v204 offset:3072
	ds_read_b128 v[160:163], v204 offset:4096
	ds_read_b128 v[164:167], v204 offset:5120
	ds_read_b128 v[168:171], v204 offset:6144
	ds_read_b128 v[172:175], v204 offset:7168
	global_load_lds_dwordx4 v[184:185], off
	s_add_i32 m0, s68, 0xe000
	s_nop 0
	global_load_lds_dwordx4 v[182:183], off
	s_waitcnt lgkmcnt(8)
	s_barrier
	s_waitcnt lgkmcnt(0)
	s_setprio 1
	s_waitcnt lgkmcnt(0)
	v_mfma_f32_16x16x32_bf16 v[124:127], v[128:131], v[144:147], 0
	v_mfma_f32_16x16x32_bf16 v[60:63], v[136:139], v[144:147], 0
	v_mfma_f32_16x16x32_bf16 v[116:119], v[128:131], v[152:155], 0
	v_mfma_f32_16x16x32_bf16 v[52:55], v[136:139], v[152:155], 0
	v_mfma_f32_16x16x32_bf16 v[108:111], v[128:131], v[160:163], 0
	v_mfma_f32_16x16x32_bf16 v[44:47], v[136:139], v[160:163], 0
	v_mfma_f32_16x16x32_bf16 v[100:103], v[128:131], v[168:171], 0
	v_mfma_f32_16x16x32_bf16 v[36:39], v[136:139], v[168:171], 0
	v_mfma_f32_16x16x32_bf16 v[124:127], v[132:135], v[148:151], v[124:127]
	v_mfma_f32_16x16x32_bf16 v[60:63], v[140:143], v[148:151], v[60:63]
	v_mfma_f32_16x16x32_bf16 v[116:119], v[132:135], v[156:159], v[116:119]
	v_mfma_f32_16x16x32_bf16 v[52:55], v[140:143], v[156:159], v[52:55]
	v_mfma_f32_16x16x32_bf16 v[108:111], v[132:135], v[164:167], v[108:111]
	v_mfma_f32_16x16x32_bf16 v[44:47], v[140:143], v[164:167], v[44:47]
	v_mfma_f32_16x16x32_bf16 v[100:103], v[132:135], v[172:175], v[100:103]
	v_mfma_f32_16x16x32_bf16 v[36:39], v[140:143], v[172:175], v[36:39]
	s_setprio 0
	s_barrier
	s_add_i32 s51, s78, s33
	v_lshl_add_u64 v[198:199], s[84:85], 0, v[178:179]
	s_mov_b32 m0, s51
	ds_read_b128 v[182:185], v205
	ds_read_b128 v[186:189], v205 offset:1024
	ds_read_b128 v[190:193], v205 offset:2048
	ds_read_b128 v[194:197], v205 offset:3072
	global_load_lds_dwordx4 v[198:199], off
	v_lshl_add_u64 v[200:201], v[198:199], 0, s[4:5]
	s_add_i32 m0, s51, 0x2000
	s_nop 0
	global_load_lds_dwordx4 v[200:201], off
	s_barrier
	s_waitcnt lgkmcnt(0)
	s_setprio 1
	s_waitcnt lgkmcnt(0)
	v_mfma_f32_16x16x32_bf16 v[120:123], v[182:185], v[144:147], 0
	v_mfma_f32_16x16x32_bf16 v[56:59], v[190:193], v[144:147], 0
	v_mfma_f32_16x16x32_bf16 v[112:115], v[182:185], v[152:155], 0
	v_mfma_f32_16x16x32_bf16 v[48:51], v[190:193], v[152:155], 0
	v_mfma_f32_16x16x32_bf16 v[104:107], v[182:185], v[160:163], 0
	v_mfma_f32_16x16x32_bf16 v[40:43], v[190:193], v[160:163], 0
	v_mfma_f32_16x16x32_bf16 v[96:99], v[182:185], v[168:171], 0
	v_mfma_f32_16x16x32_bf16 v[32:35], v[190:193], v[168:171], 0
	v_mfma_f32_16x16x32_bf16 v[120:123], v[186:189], v[148:151], v[120:123]
	v_mfma_f32_16x16x32_bf16 v[56:59], v[194:197], v[148:151], v[56:59]
	v_mfma_f32_16x16x32_bf16 v[112:115], v[186:189], v[156:159], v[112:115]
	v_mfma_f32_16x16x32_bf16 v[48:51], v[194:197], v[156:159], v[48:51]
	v_mfma_f32_16x16x32_bf16 v[104:107], v[186:189], v[164:167], v[104:107]
	v_mfma_f32_16x16x32_bf16 v[40:43], v[194:197], v[164:167], v[40:43]
	v_mfma_f32_16x16x32_bf16 v[96:99], v[186:189], v[172:175], v[96:99]
	v_mfma_f32_16x16x32_bf16 v[32:35], v[194:197], v[172:175], v[32:35]
	s_setprio 0
	s_mov_b32 m0, s68
	v_lshl_add_u64 v[200:201], s[82:83], 0, v[176:177]
	s_barrier
	ds_read_b128 v[144:147], v204 offset:16384
	ds_read_b128 v[148:151], v204 offset:17408
	ds_read_b128 v[152:155], v204 offset:18432
	ds_read_b128 v[156:159], v204 offset:19456
	ds_read_b128 v[160:163], v204 offset:20480
	ds_read_b128 v[164:167], v204 offset:21504
	ds_read_b128 v[168:171], v204 offset:22528
	ds_read_b128 v[172:175], v204 offset:23552
	global_load_lds_dwordx4 v[200:201], off
	v_lshl_add_u64 v[206:207], v[200:201], 0, s[6:7]
	s_mov_b32 m0, s69
	s_nop 0
	global_load_lds_dwordx4 v[206:207], off
	s_barrier
	s_waitcnt lgkmcnt(0)
	s_setprio 1
	s_waitcnt lgkmcnt(0)
	v_mfma_f32_16x16x32_bf16 v[92:95], v[128:131], v[144:147], 0
	v_mfma_f32_16x16x32_bf16 v[28:31], v[136:139], v[144:147], 0
	v_mfma_f32_16x16x32_bf16 v[84:87], v[128:131], v[152:155], 0
	v_mfma_f32_16x16x32_bf16 v[20:23], v[136:139], v[152:155], 0
	v_mfma_f32_16x16x32_bf16 v[80:83], v[128:131], v[160:163], 0
	v_mfma_f32_16x16x32_bf16 v[16:19], v[136:139], v[160:163], 0
	v_mfma_f32_16x16x32_bf16 v[76:79], v[128:131], v[168:171], 0
	v_mfma_f32_16x16x32_bf16 v[12:15], v[136:139], v[168:171], 0
	v_mfma_f32_16x16x32_bf16 v[92:95], v[132:135], v[148:151], v[92:95]
	v_mfma_f32_16x16x32_bf16 v[28:31], v[140:143], v[148:151], v[28:31]
	v_mfma_f32_16x16x32_bf16 v[84:87], v[132:135], v[156:159], v[84:87]
	v_mfma_f32_16x16x32_bf16 v[20:23], v[140:143], v[156:159], v[20:23]
	v_mfma_f32_16x16x32_bf16 v[80:83], v[132:135], v[164:167], v[80:83]
	v_mfma_f32_16x16x32_bf16 v[16:19], v[140:143], v[164:167], v[16:19]
	v_mfma_f32_16x16x32_bf16 v[76:79], v[132:135], v[172:175], v[76:79]
	v_mfma_f32_16x16x32_bf16 v[12:15], v[140:143], v[172:175], v[12:15]
	s_setprio 0
	s_barrier
	s_add_i32 s51, s79, s33
	v_lshl_add_u64 v[128:129], v[198:199], 0, s[6:7]
	s_mov_b32 m0, s51
	s_nop 0
	global_load_lds_dwordx4 v[128:129], off
	v_lshl_add_u64 v[128:129], v[198:199], 0, s[8:9]
	s_add_i32 m0, s51, 0x2000
	s_nop 0
	global_load_lds_dwordx4 v[128:129], off
	s_waitcnt vmcnt(6)
	s_barrier
	s_setprio 1
	v_mfma_f32_16x16x32_bf16 v[88:91], v[182:185], v[144:147], 0
	v_mfma_f32_16x16x32_bf16 v[24:27], v[190:193], v[144:147], 0
	v_mfma_f32_16x16x32_bf16 v[72:75], v[182:185], v[152:155], 0
	v_mfma_f32_16x16x32_bf16 v[8:11], v[190:193], v[152:155], 0
	v_mfma_f32_16x16x32_bf16 v[68:71], v[182:185], v[160:163], 0
	v_mfma_f32_16x16x32_bf16 v[4:7], v[190:193], v[160:163], 0
	v_mfma_f32_16x16x32_bf16 v[64:67], v[182:185], v[168:171], 0
	v_mfma_f32_16x16x32_bf16 v[0:3], v[190:193], v[168:171], 0
	v_mfma_f32_16x16x32_bf16 v[88:91], v[186:189], v[148:151], v[88:91]
	v_mfma_f32_16x16x32_bf16 v[24:27], v[194:197], v[148:151], v[24:27]
	v_mfma_f32_16x16x32_bf16 v[72:75], v[186:189], v[156:159], v[72:75]
	v_mfma_f32_16x16x32_bf16 v[8:11], v[194:197], v[156:159], v[8:11]
	v_mfma_f32_16x16x32_bf16 v[68:71], v[186:189], v[164:167], v[68:71]
	v_mfma_f32_16x16x32_bf16 v[4:7], v[194:197], v[164:167], v[4:7]
	v_mfma_f32_16x16x32_bf16 v[64:67], v[186:189], v[172:175], v[64:67]
	v_mfma_f32_16x16x32_bf16 v[0:3], v[194:197], v[172:175], v[0:3]
	s_setprio 0
	s_add_i32 s51, 0, 0x18000
	v_add_u32_e32 v140, s51, v202
	s_barrier
	ds_read_b128 v[128:131], v140
	ds_read_b128 v[132:135], v140 offset:1024
	ds_read_b128 v[136:139], v140 offset:2048
	ds_read_b128 v[140:143], v140 offset:3072
	s_mov_b64 s[82:83], 0x2000
	s_mov_b32 m0, s70
	v_lshl_add_u64 v[182:183], v[200:201], 0, s[82:83]
	s_mov_b64 s[82:83], 0x42000
	ds_read_b128 v[144:147], v204 offset:32768
	ds_read_b128 v[148:151], v204 offset:33792
	ds_read_b128 v[152:155], v204 offset:34816
	ds_read_b128 v[156:159], v204 offset:35840
	ds_read_b128 v[160:163], v204 offset:36864
	ds_read_b128 v[164:167], v204 offset:37888
	ds_read_b128 v[168:171], v204 offset:38912
	ds_read_b128 v[172:175], v204 offset:39936
	global_load_lds_dwordx4 v[182:183], off
	v_lshl_add_u64 v[182:183], v[200:201], 0, s[82:83]
	s_mov_b32 m0, s71
	s_nop 0
	global_load_lds_dwordx4 v[182:183], off
	s_waitcnt lgkmcnt(8)
	s_barrier
	s_waitcnt lgkmcnt(0)
	s_setprio 1
	s_waitcnt lgkmcnt(0)
	v_mfma_f32_16x16x32_bf16 v[124:127], v[128:131], v[144:147], v[124:127]
	v_mfma_f32_16x16x32_bf16 v[60:63], v[136:139], v[144:147], v[60:63]
	v_mfma_f32_16x16x32_bf16 v[116:119], v[128:131], v[152:155], v[116:119]
	v_mfma_f32_16x16x32_bf16 v[52:55], v[136:139], v[152:155], v[52:55]
	v_mfma_f32_16x16x32_bf16 v[108:111], v[128:131], v[160:163], v[108:111]
	v_mfma_f32_16x16x32_bf16 v[44:47], v[136:139], v[160:163], v[44:47]
	v_mfma_f32_16x16x32_bf16 v[100:103], v[128:131], v[168:171], v[100:103]
	v_mfma_f32_16x16x32_bf16 v[36:39], v[136:139], v[168:171], v[36:39]
	v_mfma_f32_16x16x32_bf16 v[124:127], v[132:135], v[148:151], v[124:127]
	v_mfma_f32_16x16x32_bf16 v[60:63], v[140:143], v[148:151], v[60:63]
	v_mfma_f32_16x16x32_bf16 v[116:119], v[132:135], v[156:159], v[116:119]
	v_mfma_f32_16x16x32_bf16 v[52:55], v[140:143], v[156:159], v[52:55]
	v_mfma_f32_16x16x32_bf16 v[108:111], v[132:135], v[164:167], v[108:111]
	v_mfma_f32_16x16x32_bf16 v[44:47], v[140:143], v[164:167], v[44:47]
	v_mfma_f32_16x16x32_bf16 v[100:103], v[132:135], v[172:175], v[100:103]
	v_mfma_f32_16x16x32_bf16 v[36:39], v[140:143], v[172:175], v[36:39]
	s_setprio 0
	s_barrier
	s_add_i32 s81, 0, 0x1c000
	s_add_i32 s51, s51, s33
	v_add_u32_e32 v194, s81, v202
	v_lshl_add_u64 v[206:207], v[198:199], 0, s[16:17]
	s_mov_b32 m0, s51
	ds_read_b128 v[182:185], v194
	ds_read_b128 v[186:189], v194 offset:1024
	ds_read_b128 v[190:193], v194 offset:2048
	ds_read_b128 v[194:197], v194 offset:3072
	global_load_lds_dwordx4 v[206:207], off
	v_lshl_add_u64 v[206:207], v[198:199], 0, s[30:31]
	s_add_i32 m0, s51, 0x2000
	s_nop 0
	global_load_lds_dwordx4 v[206:207], off
	s_barrier
	s_waitcnt lgkmcnt(0)
	s_setprio 1
	s_waitcnt lgkmcnt(0)
	v_mfma_f32_16x16x32_bf16 v[120:123], v[182:185], v[144:147], v[120:123]
	v_mfma_f32_16x16x32_bf16 v[56:59], v[190:193], v[144:147], v[56:59]
	v_mfma_f32_16x16x32_bf16 v[112:115], v[182:185], v[152:155], v[112:115]
	v_mfma_f32_16x16x32_bf16 v[48:51], v[190:193], v[152:155], v[48:51]
	v_mfma_f32_16x16x32_bf16 v[104:107], v[182:185], v[160:163], v[104:107]
	v_mfma_f32_16x16x32_bf16 v[40:43], v[190:193], v[160:163], v[40:43]
	v_mfma_f32_16x16x32_bf16 v[96:99], v[182:185], v[168:171], v[96:99]
	v_mfma_f32_16x16x32_bf16 v[32:35], v[190:193], v[168:171], v[32:35]
	v_mfma_f32_16x16x32_bf16 v[120:123], v[186:189], v[148:151], v[120:123]
	v_mfma_f32_16x16x32_bf16 v[56:59], v[194:197], v[148:151], v[56:59]
	v_mfma_f32_16x16x32_bf16 v[112:115], v[186:189], v[156:159], v[112:115]
	v_mfma_f32_16x16x32_bf16 v[48:51], v[194:197], v[156:159], v[48:51]
	v_mfma_f32_16x16x32_bf16 v[104:107], v[186:189], v[164:167], v[104:107]
	v_mfma_f32_16x16x32_bf16 v[40:43], v[194:197], v[164:167], v[40:43]
	v_mfma_f32_16x16x32_bf16 v[96:99], v[186:189], v[172:175], v[96:99]
	v_mfma_f32_16x16x32_bf16 v[32:35], v[194:197], v[172:175], v[32:35]
	s_setprio 0
	s_mov_b32 m0, s75
	v_lshl_add_u64 v[206:207], v[200:201], 0, s[16:17]
	s_barrier
	ds_read_b128 v[144:147], v204 offset:49152
	ds_read_b128 v[148:151], v204 offset:50176
	ds_read_b128 v[152:155], v204 offset:51200
	ds_read_b128 v[156:159], v204 offset:52224
	ds_read_b128 v[160:163], v204 offset:53248
	ds_read_b128 v[164:167], v204 offset:54272
	ds_read_b128 v[168:171], v204 offset:55296
	ds_read_b128 v[172:175], v204 offset:56320
	global_load_lds_dwordx4 v[206:207], off
	v_lshl_add_u64 v[200:201], v[200:201], 0, s[38:39]
	s_mov_b32 m0, s76
	s_nop 0
	global_load_lds_dwordx4 v[200:201], off
	s_barrier
	s_waitcnt lgkmcnt(0)
	s_setprio 1
	s_waitcnt lgkmcnt(0)
	v_mfma_f32_16x16x32_bf16 v[92:95], v[128:131], v[144:147], v[92:95]
	v_mfma_f32_16x16x32_bf16 v[28:31], v[136:139], v[144:147], v[28:31]
	v_mfma_f32_16x16x32_bf16 v[84:87], v[128:131], v[152:155], v[84:87]
	v_mfma_f32_16x16x32_bf16 v[20:23], v[136:139], v[152:155], v[20:23]
	v_mfma_f32_16x16x32_bf16 v[80:83], v[128:131], v[160:163], v[80:83]
	v_mfma_f32_16x16x32_bf16 v[16:19], v[136:139], v[160:163], v[16:19]
	v_mfma_f32_16x16x32_bf16 v[76:79], v[128:131], v[168:171], v[76:79]
	v_mfma_f32_16x16x32_bf16 v[12:15], v[136:139], v[168:171], v[12:15]
	v_mfma_f32_16x16x32_bf16 v[92:95], v[132:135], v[148:151], v[92:95]
	v_mfma_f32_16x16x32_bf16 v[28:31], v[140:143], v[148:151], v[28:31]
	v_mfma_f32_16x16x32_bf16 v[84:87], v[132:135], v[156:159], v[84:87]
	v_mfma_f32_16x16x32_bf16 v[20:23], v[140:143], v[156:159], v[20:23]
	v_mfma_f32_16x16x32_bf16 v[80:83], v[132:135], v[164:167], v[80:83]
	v_mfma_f32_16x16x32_bf16 v[16:19], v[140:143], v[164:167], v[16:19]
	v_mfma_f32_16x16x32_bf16 v[76:79], v[132:135], v[172:175], v[76:79]
	v_mfma_f32_16x16x32_bf16 v[12:15], v[140:143], v[172:175], v[12:15]
	s_setprio 0
	s_barrier
	s_add_i32 s51, s81, s33
	v_lshl_add_u64 v[128:129], v[198:199], 0, s[38:39]
	s_mov_b32 m0, s51
	s_nop 0
	global_load_lds_dwordx4 v[128:129], off
	v_lshl_add_u64 v[128:129], v[198:199], 0, s[40:41]
	s_add_i32 m0, s51, 0x2000
	s_nop 0
	global_load_lds_dwordx4 v[128:129], off
	s_waitcnt vmcnt(6)
	s_barrier
	s_setprio 1
	v_mfma_f32_16x16x32_bf16 v[88:91], v[182:185], v[144:147], v[88:91]
	v_mfma_f32_16x16x32_bf16 v[24:27], v[190:193], v[144:147], v[24:27]
	v_mfma_f32_16x16x32_bf16 v[72:75], v[182:185], v[152:155], v[72:75]
	v_mfma_f32_16x16x32_bf16 v[8:11], v[190:193], v[152:155], v[8:11]
	v_mfma_f32_16x16x32_bf16 v[68:71], v[182:185], v[160:163], v[68:71]
	v_mfma_f32_16x16x32_bf16 v[4:7], v[190:193], v[160:163], v[4:7]
	v_mfma_f32_16x16x32_bf16 v[64:67], v[182:185], v[168:171], v[64:67]
	v_mfma_f32_16x16x32_bf16 v[0:3], v[190:193], v[168:171], v[0:3]
	v_mfma_f32_16x16x32_bf16 v[88:91], v[186:189], v[148:151], v[88:91]
	v_mfma_f32_16x16x32_bf16 v[24:27], v[194:197], v[148:151], v[24:27]
	v_mfma_f32_16x16x32_bf16 v[72:75], v[186:189], v[156:159], v[72:75]
	v_mfma_f32_16x16x32_bf16 v[8:11], v[194:197], v[156:159], v[8:11]
	v_mfma_f32_16x16x32_bf16 v[68:71], v[186:189], v[164:167], v[68:71]
	v_mfma_f32_16x16x32_bf16 v[4:7], v[194:197], v[164:167], v[4:7]
	v_mfma_f32_16x16x32_bf16 v[64:67], v[186:189], v[172:175], v[64:67]
	v_mfma_f32_16x16x32_bf16 v[0:3], v[194:197], v[172:175], v[0:3]
	s_setprio 0
	s_add_i32 s45, s45, 2
	s_add_u32 s2, s2, 0x100
	s_addc_u32 s3, s3, 0
	s_add_u32 s18, s18, 0x100
	s_addc_u32 s19, s19, 0
	s_cmp_gt_u32 s45, 13
	s_barrier

.LBB0_2187:
	s_add_u32 s26, s26, 0xa8080
	s_addc_u32 s27, s27, 0
	s_add_u32 s28, s28, 0x100
	s_addc_u32 s29, s29, 0
	s_mov_b32 s42, -2
	ds_read_b128 v[136:139], v195
	ds_read_b128 v[140:143], v195 offset:1024
	ds_read_b128 v[144:147], v195 offset:2048
	ds_read_b128 v[148:151], v195 offset:3072
	s_add_u32 s43, s26, 0xfff58080
	s_addc_u32 s44, s27, -1
	s_cmp_eq_u32 s42, 38
	s_cselect_b32 s45, s23, s44
	s_cselect_b32 s44, s22, s43
	s_cselect_b32 s59, s25, s29
	s_cselect_b32 s58, s24, s28
	v_lshl_add_u64 v[184:185], s[26:27], 0, v[130:131]
	s_add_i32 m0, s36, 0xc000
	ds_read_b128 v[152:155], v196
	ds_read_b128 v[156:159], v196 offset:1024
	ds_read_b128 v[160:163], v196 offset:2048
	ds_read_b128 v[164:167], v196 offset:3072
	ds_read_b128 v[168:171], v196 offset:4096
	ds_read_b128 v[172:175], v196 offset:5120
	ds_read_b128 v[176:179], v196 offset:6144
	ds_read_b128 v[180:183], v196 offset:7168
	global_load_lds_dwordx4 v[184:185], off
	v_lshl_add_u64 v[184:185], v[184:185], 0, s[6:7]
	s_add_i32 m0, s36, 0xe000
	s_nop 0
	global_load_lds_dwordx4 v[184:185], off
	s_waitcnt lgkmcnt(8)
	s_barrier
	s_waitcnt lgkmcnt(0)
	s_setprio 1
	s_waitcnt lgkmcnt(0)
	v_mfma_f32_16x16x32_bf16 v[124:127], v[136:139], v[152:155], 0
	v_mfma_f32_16x16x32_bf16 v[120:123], v[144:147], v[152:155], 0
	v_mfma_f32_16x16x32_bf16 v[112:115], v[136:139], v[160:163], 0
	v_mfma_f32_16x16x32_bf16 v[104:107], v[144:147], v[160:163], 0
	v_mfma_f32_16x16x32_bf16 v[96:99], v[136:139], v[168:171], 0
	v_mfma_f32_16x16x32_bf16 v[88:91], v[144:147], v[168:171], 0
	v_mfma_f32_16x16x32_bf16 v[80:83], v[136:139], v[176:179], 0
	v_mfma_f32_16x16x32_bf16 v[72:75], v[144:147], v[176:179], 0
	v_mfma_f32_16x16x32_bf16 v[124:127], v[140:143], v[156:159], v[124:127]
	v_mfma_f32_16x16x32_bf16 v[120:123], v[148:151], v[156:159], v[120:123]
	v_mfma_f32_16x16x32_bf16 v[112:115], v[140:143], v[164:167], v[112:115]
	v_mfma_f32_16x16x32_bf16 v[104:107], v[148:151], v[164:167], v[104:107]
	v_mfma_f32_16x16x32_bf16 v[96:99], v[140:143], v[172:175], v[96:99]
	v_mfma_f32_16x16x32_bf16 v[88:91], v[148:151], v[172:175], v[88:91]
	v_mfma_f32_16x16x32_bf16 v[80:83], v[140:143], v[180:183], v[80:83]
	v_mfma_f32_16x16x32_bf16 v[72:75], v[148:151], v[180:183], v[72:75]
	s_setprio 0
	s_barrier
	s_add_i32 s43, s51, s35
	v_lshl_add_u64 v[192:193], s[58:59], 0, v[128:129]
	s_mov_b32 m0, s43
	ds_read_b128 v[184:187], v197
	ds_read_b128 v[188:191], v197 offset:1024
	ds_read_b128 v[198:201], v197 offset:2048
	ds_read_b128 v[202:205], v197 offset:3072
	global_load_lds_dwordx4 v[192:193], off
	v_lshl_add_u64 v[206:207], v[192:193], 0, s[6:7]
	s_add_i32 m0, s43, 0x2000
	s_nop 0
	global_load_lds_dwordx4 v[206:207], off
	s_barrier
	s_waitcnt lgkmcnt(0)
	s_setprio 1
	s_waitcnt lgkmcnt(0)
	v_mfma_f32_16x16x32_bf16 v[116:119], v[184:187], v[152:155], 0
	v_mfma_f32_16x16x32_bf16 v[108:111], v[198:201], v[152:155], 0
	v_mfma_f32_16x16x32_bf16 v[100:103], v[184:187], v[160:163], 0
	v_mfma_f32_16x16x32_bf16 v[92:95], v[198:201], v[160:163], 0
	v_mfma_f32_16x16x32_bf16 v[84:87], v[184:187], v[168:171], 0
	v_mfma_f32_16x16x32_bf16 v[76:79], v[198:201], v[168:171], 0
	v_mfma_f32_16x16x32_bf16 v[68:71], v[184:187], v[176:179], 0
	v_mfma_f32_16x16x32_bf16 v[64:67], v[198:201], v[176:179], 0
	v_mfma_f32_16x16x32_bf16 v[116:119], v[188:191], v[156:159], v[116:119]
	v_mfma_f32_16x16x32_bf16 v[108:111], v[202:205], v[156:159], v[108:111]
	v_mfma_f32_16x16x32_bf16 v[100:103], v[188:191], v[164:167], v[100:103]
	v_mfma_f32_16x16x32_bf16 v[92:95], v[202:205], v[164:167], v[92:95]
	v_mfma_f32_16x16x32_bf16 v[84:87], v[188:191], v[172:175], v[84:87]
	v_mfma_f32_16x16x32_bf16 v[76:79], v[202:205], v[172:175], v[76:79]
	v_mfma_f32_16x16x32_bf16 v[68:71], v[188:191], v[180:183], v[68:71]
	v_mfma_f32_16x16x32_bf16 v[64:67], v[202:205], v[180:183], v[64:67]
	s_setprio 0
	s_mov_b32 m0, s36
	v_lshl_add_u64 v[206:207], s[44:45], 0, v[128:129]
	s_barrier
	ds_read_b128 v[152:155], v196 offset:16384
	ds_read_b128 v[156:159], v196 offset:17408
	ds_read_b128 v[160:163], v196 offset:18432
	ds_read_b128 v[164:167], v196 offset:19456
	ds_read_b128 v[168:171], v196 offset:20480
	ds_read_b128 v[172:175], v196 offset:21504
	ds_read_b128 v[176:179], v196 offset:22528
	ds_read_b128 v[180:183], v196 offset:23552
	global_load_lds_dwordx4 v[206:207], off
	v_lshl_add_u64 v[208:209], v[206:207], 0, s[6:7]
	s_mov_b32 m0, s37
	s_nop 0
	global_load_lds_dwordx4 v[208:209], off
	s_barrier
	s_waitcnt lgkmcnt(0)
	s_setprio 1
	s_waitcnt lgkmcnt(0)
	v_mfma_f32_16x16x32_bf16 v[60:63], v[136:139], v[152:155], 0
	v_mfma_f32_16x16x32_bf16 v[56:59], v[144:147], v[152:155], 0
	v_mfma_f32_16x16x32_bf16 v[48:51], v[136:139], v[160:163], 0
	v_mfma_f32_16x16x32_bf16 v[40:43], v[144:147], v[160:163], 0
	v_mfma_f32_16x16x32_bf16 v[32:35], v[136:139], v[168:171], 0
	v_mfma_f32_16x16x32_bf16 v[24:27], v[144:147], v[168:171], 0
	v_mfma_f32_16x16x32_bf16 v[16:19], v[136:139], v[176:179], 0
	v_mfma_f32_16x16x32_bf16 v[8:11], v[144:147], v[176:179], 0
	v_mfma_f32_16x16x32_bf16 v[60:63], v[140:143], v[156:159], v[60:63]
	v_mfma_f32_16x16x32_bf16 v[56:59], v[148:151], v[156:159], v[56:59]
	v_mfma_f32_16x16x32_bf16 v[48:51], v[140:143], v[164:167], v[48:51]
	v_mfma_f32_16x16x32_bf16 v[40:43], v[148:151], v[164:167], v[40:43]
	v_mfma_f32_16x16x32_bf16 v[32:35], v[140:143], v[172:175], v[32:35]
	v_mfma_f32_16x16x32_bf16 v[24:27], v[148:151], v[172:175], v[24:27]
	v_mfma_f32_16x16x32_bf16 v[16:19], v[140:143], v[180:183], v[16:19]
	v_mfma_f32_16x16x32_bf16 v[8:11], v[148:151], v[180:183], v[8:11]
	s_setprio 0
	s_barrier
	s_add_i32 s43, s52, s35
	v_lshl_add_u64 v[136:137], v[192:193], 0, s[8:9]
	s_mov_b32 m0, s43
	s_nop 0
	global_load_lds_dwordx4 v[136:137], off
	v_lshl_add_u64 v[136:137], v[192:193], 0, s[10:11]
	s_add_i32 m0, s43, 0x2000
	s_nop 0
	global_load_lds_dwordx4 v[136:137], off
	s_waitcnt vmcnt(6)
	s_barrier
	s_setprio 1
	v_mfma_f32_16x16x32_bf16 v[52:55], v[184:187], v[152:155], 0
	v_mfma_f32_16x16x32_bf16 v[44:47], v[198:201], v[152:155], 0
	v_mfma_f32_16x16x32_bf16 v[36:39], v[184:187], v[160:163], 0
	v_mfma_f32_16x16x32_bf16 v[28:31], v[198:201], v[160:163], 0
	v_mfma_f32_16x16x32_bf16 v[20:23], v[184:187], v[168:171], 0
	v_mfma_f32_16x16x32_bf16 v[12:15], v[198:201], v[168:171], 0
	v_mfma_f32_16x16x32_bf16 v[4:7], v[184:187], v[176:179], 0
	v_mfma_f32_16x16x32_bf16 v[0:3], v[198:201], v[176:179], 0
	v_mfma_f32_16x16x32_bf16 v[52:55], v[188:191], v[156:159], v[52:55]
	v_mfma_f32_16x16x32_bf16 v[44:47], v[202:205], v[156:159], v[44:47]
	v_mfma_f32_16x16x32_bf16 v[36:39], v[188:191], v[164:167], v[36:39]
	v_mfma_f32_16x16x32_bf16 v[28:31], v[202:205], v[164:167], v[28:31]
	v_mfma_f32_16x16x32_bf16 v[20:23], v[188:191], v[172:175], v[20:23]
	v_mfma_f32_16x16x32_bf16 v[12:15], v[202:205], v[172:175], v[12:15]
	v_mfma_f32_16x16x32_bf16 v[4:7], v[188:191], v[180:183], v[4:7]
	v_mfma_f32_16x16x32_bf16 v[0:3], v[202:205], v[180:183], v[0:3]
	s_setprio 0
	s_add_i32 s43, 0, 0x18000
	v_add_u32_e32 v148, s43, v194
	s_barrier
	ds_read_b128 v[136:139], v148
	ds_read_b128 v[140:143], v148 offset:1024
	ds_read_b128 v[144:147], v148 offset:2048
	ds_read_b128 v[148:151], v148 offset:3072
	s_mov_b32 m0, s38
	v_lshl_add_u64 v[184:185], v[206:207], 0, s[8:9]
	ds_read_b128 v[152:155], v196 offset:32768
	ds_read_b128 v[156:159], v196 offset:33792
	ds_read_b128 v[160:163], v196 offset:34816
	ds_read_b128 v[164:167], v196 offset:35840
	ds_read_b128 v[168:171], v196 offset:36864
	ds_read_b128 v[172:175], v196 offset:37888
	ds_read_b128 v[176:179], v196 offset:38912
	ds_read_b128 v[180:183], v196 offset:39936
	global_load_lds_dwordx4 v[184:185], off
	v_lshl_add_u64 v[184:185], v[206:207], 0, s[10:11]
	s_mov_b32 m0, s39
	s_nop 0
	global_load_lds_dwordx4 v[184:185], off
	s_waitcnt lgkmcnt(8)
	s_barrier
	s_waitcnt lgkmcnt(0)
	s_setprio 1
	s_waitcnt lgkmcnt(0)
	v_mfma_f32_16x16x32_bf16 v[124:127], v[136:139], v[152:155], v[124:127]
	v_mfma_f32_16x16x32_bf16 v[120:123], v[144:147], v[152:155], v[120:123]
	v_mfma_f32_16x16x32_bf16 v[112:115], v[136:139], v[160:163], v[112:115]
	v_mfma_f32_16x16x32_bf16 v[104:107], v[144:147], v[160:163], v[104:107]
	v_mfma_f32_16x16x32_bf16 v[96:99], v[136:139], v[168:171], v[96:99]
	v_mfma_f32_16x16x32_bf16 v[88:91], v[144:147], v[168:171], v[88:91]
	v_mfma_f32_16x16x32_bf16 v[80:83], v[136:139], v[176:179], v[80:83]
	v_mfma_f32_16x16x32_bf16 v[72:75], v[144:147], v[176:179], v[72:75]
	v_mfma_f32_16x16x32_bf16 v[124:127], v[140:143], v[156:159], v[124:127]
	v_mfma_f32_16x16x32_bf16 v[120:123], v[148:151], v[156:159], v[120:123]
	v_mfma_f32_16x16x32_bf16 v[112:115], v[140:143], v[164:167], v[112:115]
	v_mfma_f32_16x16x32_bf16 v[104:107], v[148:151], v[164:167], v[104:107]
	v_mfma_f32_16x16x32_bf16 v[96:99], v[140:143], v[172:175], v[96:99]
	v_mfma_f32_16x16x32_bf16 v[88:91], v[148:151], v[172:175], v[88:91]
	v_mfma_f32_16x16x32_bf16 v[80:83], v[140:143], v[180:183], v[80:83]
	v_mfma_f32_16x16x32_bf16 v[72:75], v[148:151], v[180:183], v[72:75]
	s_setprio 0
	s_barrier
	s_add_i32 s44, 0, 0x1c000
	s_add_i32 s43, s43, s35
	v_add_u32_e32 v202, s44, v194
	v_lshl_add_u64 v[208:209], v[192:193], 0, s[12:13]
	s_mov_b32 m0, s43
	ds_read_b128 v[184:187], v202
	ds_read_b128 v[188:191], v202 offset:1024
	ds_read_b128 v[198:201], v202 offset:2048
	ds_read_b128 v[202:205], v202 offset:3072
	global_load_lds_dwordx4 v[208:209], off
	v_lshl_add_u64 v[208:209], v[192:193], 0, s[14:15]
	s_add_i32 m0, s43, 0x2000
	s_nop 0
	global_load_lds_dwordx4 v[208:209], off
	s_barrier
	s_waitcnt lgkmcnt(0)
	s_setprio 1
	s_waitcnt lgkmcnt(0)
	v_mfma_f32_16x16x32_bf16 v[116:119], v[184:187], v[152:155], v[116:119]
	v_mfma_f32_16x16x32_bf16 v[108:111], v[198:201], v[152:155], v[108:111]
	v_mfma_f32_16x16x32_bf16 v[100:103], v[184:187], v[160:163], v[100:103]
	v_mfma_f32_16x16x32_bf16 v[92:95], v[198:201], v[160:163], v[92:95]
	v_mfma_f32_16x16x32_bf16 v[84:87], v[184:187], v[168:171], v[84:87]
	v_mfma_f32_16x16x32_bf16 v[76:79], v[198:201], v[168:171], v[76:79]
	v_mfma_f32_16x16x32_bf16 v[68:71], v[184:187], v[176:179], v[68:71]
	v_mfma_f32_16x16x32_bf16 v[64:67], v[198:201], v[176:179], v[64:67]
	v_mfma_f32_16x16x32_bf16 v[116:119], v[188:191], v[156:159], v[116:119]
	v_mfma_f32_16x16x32_bf16 v[108:111], v[202:205], v[156:159], v[108:111]
	v_mfma_f32_16x16x32_bf16 v[100:103], v[188:191], v[164:167], v[100:103]
	v_mfma_f32_16x16x32_bf16 v[92:95], v[202:205], v[164:167], v[92:95]
	v_mfma_f32_16x16x32_bf16 v[84:87], v[188:191], v[172:175], v[84:87]
	v_mfma_f32_16x16x32_bf16 v[76:79], v[202:205], v[172:175], v[76:79]
	v_mfma_f32_16x16x32_bf16 v[68:71], v[188:191], v[180:183], v[68:71]
	v_mfma_f32_16x16x32_bf16 v[64:67], v[202:205], v[180:183], v[64:67]
	s_setprio 0
	s_mov_b32 m0, s49
	v_lshl_add_u64 v[208:209], v[206:207], 0, s[12:13]
	s_barrier
	ds_read_b128 v[152:155], v196 offset:49152
	ds_read_b128 v[156:159], v196 offset:50176
	ds_read_b128 v[160:163], v196 offset:51200
	ds_read_b128 v[164:167], v196 offset:52224
	ds_read_b128 v[168:171], v196 offset:53248
	ds_read_b128 v[172:175], v196 offset:54272
	ds_read_b128 v[176:179], v196 offset:55296
	ds_read_b128 v[180:183], v196 offset:56320
	global_load_lds_dwordx4 v[208:209], off
	v_lshl_add_u64 v[206:207], v[206:207], 0, s[14:15]
	s_mov_b32 m0, s50
	s_nop 0
	global_load_lds_dwordx4 v[206:207], off
	s_barrier
	s_waitcnt lgkmcnt(0)
	s_setprio 1
	s_waitcnt lgkmcnt(0)
	v_mfma_f32_16x16x32_bf16 v[60:63], v[136:139], v[152:155], v[60:63]
	v_mfma_f32_16x16x32_bf16 v[56:59], v[144:147], v[152:155], v[56:59]
	v_mfma_f32_16x16x32_bf16 v[48:51], v[136:139], v[160:163], v[48:51]
	v_mfma_f32_16x16x32_bf16 v[40:43], v[144:147], v[160:163], v[40:43]
	v_mfma_f32_16x16x32_bf16 v[32:35], v[136:139], v[168:171], v[32:35]
	v_mfma_f32_16x16x32_bf16 v[24:27], v[144:147], v[168:171], v[24:27]
	v_mfma_f32_16x16x32_bf16 v[16:19], v[136:139], v[176:179], v[16:19]
	v_mfma_f32_16x16x32_bf16 v[8:11], v[144:147], v[176:179], v[8:11]
	v_mfma_f32_16x16x32_bf16 v[60:63], v[140:143], v[156:159], v[60:63]
	v_mfma_f32_16x16x32_bf16 v[56:59], v[148:151], v[156:159], v[56:59]
	v_mfma_f32_16x16x32_bf16 v[48:51], v[140:143], v[164:167], v[48:51]
	v_mfma_f32_16x16x32_bf16 v[40:43], v[148:151], v[164:167], v[40:43]
	v_mfma_f32_16x16x32_bf16 v[32:35], v[140:143], v[172:175], v[32:35]
	v_mfma_f32_16x16x32_bf16 v[24:27], v[148:151], v[172:175], v[24:27]
	v_mfma_f32_16x16x32_bf16 v[16:19], v[140:143], v[180:183], v[16:19]
	v_mfma_f32_16x16x32_bf16 v[8:11], v[148:151], v[180:183], v[8:11]
	s_setprio 0
	s_barrier
	s_add_i32 s43, s44, s35
	v_lshl_add_u64 v[136:137], v[192:193], 0, s[16:17]
	s_mov_b32 m0, s43
	s_nop 0
	global_load_lds_dwordx4 v[136:137], off
	v_lshl_add_u64 v[136:137], v[192:193], 0, s[18:19]
	s_add_i32 m0, s43, 0x2000
	s_nop 0
	global_load_lds_dwordx4 v[136:137], off
	s_waitcnt vmcnt(6)
	s_barrier
	s_setprio 1
	v_mfma_f32_16x16x32_bf16 v[52:55], v[184:187], v[152:155], v[52:55]
	v_mfma_f32_16x16x32_bf16 v[44:47], v[198:201], v[152:155], v[44:47]
	v_mfma_f32_16x16x32_bf16 v[36:39], v[184:187], v[160:163], v[36:39]
	v_mfma_f32_16x16x32_bf16 v[28:31], v[198:201], v[160:163], v[28:31]
	v_mfma_f32_16x16x32_bf16 v[20:23], v[184:187], v[168:171], v[20:23]
	v_mfma_f32_16x16x32_bf16 v[12:15], v[198:201], v[168:171], v[12:15]
	v_mfma_f32_16x16x32_bf16 v[4:7], v[184:187], v[176:179], v[4:7]
	v_mfma_f32_16x16x32_bf16 v[0:3], v[198:201], v[176:179], v[0:3]
	v_mfma_f32_16x16x32_bf16 v[52:55], v[188:191], v[156:159], v[52:55]
	v_mfma_f32_16x16x32_bf16 v[44:47], v[202:205], v[156:159], v[44:47]
	v_mfma_f32_16x16x32_bf16 v[36:39], v[188:191], v[164:167], v[36:39]
	v_mfma_f32_16x16x32_bf16 v[28:31], v[202:205], v[164:167], v[28:31]
	v_mfma_f32_16x16x32_bf16 v[20:23], v[188:191], v[172:175], v[20:23]
	v_mfma_f32_16x16x32_bf16 v[12:15], v[202:205], v[172:175], v[12:15]
	v_mfma_f32_16x16x32_bf16 v[4:7], v[188:191], v[180:183], v[4:7]
	v_mfma_f32_16x16x32_bf16 v[0:3], v[202:205], v[180:183], v[0:3]
	s_setprio 0
	s_add_i32 s42, s42, 2
	s_add_u32 s26, s26, 0x100
	s_addc_u32 s27, s27, 0
	s_add_u32 s28, s28, 0x100
	s_addc_u32 s29, s29, 0
	s_cmp_gt_u32 s42, 39
	s_barrier
